# compiler-layout pipelined norms with 16-byte device-scope stores, plus device-scope stores in residual, GU, in-proj, final and init epilogues
# speedup vs baseline: 1.0132x; 1.0102x over previous
; __device__ __forceinline__ void store8bf(bf16_t* p, f32x4 v0, f32x4 v1) { u32x4 w; w.x = cvt_pk_bf16(v0[0], v0[1]); w.y = cvt_pk_bf16(v0[2], v0[3]); w.z = cvt_pk_bf16(v1[0], v1[1]); w.w = cvt_pk_bf16(v1[2], v1[3]); *(u32x4*)p = w; }
; template <int M> __device__ __forceinline__ float shx(float v) { return __builtin_bit_cast(float, __builtin_amdgcn_ds_swizzle(__builtin_bit_cast(int, v), (M << 10) | 0x1f)); }
; __device__ __forceinline__ float xhalf(float v) {
;   int l = (int)__builtin_amdgcn_mbcnt_hi(~0u, __builtin_amdgcn_mbcnt_lo(~0u, 0u)); asm volatile("" : "+v"(l));
;   return __builtin_bit_cast(float, __builtin_amdgcn_ds_bpermute((l ^ 32) << 2, __builtin_bit_cast(int, v))); }
; __device__ __forceinline__ float sum32(float v) { return v + xhalf(v); }
; __device__ __forceinline__ float max32(float v) { return __builtin_fmaxf(v, xhalf(v)); }
; __device__ __forceinline__ float wave_sum(float v) {
;   v += shx<16>(v); v += shx<8>(v); v += shx<4>(v); v += shx<2>(v); v += shx<1>(v); return sum32(v);
; }
; __device__ __forceinline__ void norm_phase(const float* H, const float* g, bf16_t* HN) {
;     ...
;   for (int row = gw; row < NREAL + 64; row += 2 * nw) {
;     const int row2 = row + nw < NREAL + 64 ? row + nw : row;
;     const float* p = H + (size_t)row * DM + lane * 8; const float* p2 = H + (size_t)row2 * DM + lane * 8; f32x4 v[4], u[4]; float ss = 0.f, ss2 = 0.f;
; #pragma unroll
;     for (int i = 0; i < 4; ++i) { v[i] = *(const f32x4*)(p + 512 * (i >> 1) + 4 * (i & 1)); u[i] = *(const f32x4*)(p2 + 512 * (i >> 1) + 4 * (i & 1)); }
; #pragma unroll
;     for (int i = 0; i < 4; ++i) { ss += v[i][0] * v[i][0] + v[i][1] * v[i][1] + v[i][2] * v[i][2] + v[i][3] * v[i][3]; ss2 += u[i][0] * u[i][0] + u[i][1] * u[i][1] + u[i][2] * u[i][2] + u[i][3] * u[i][3]; }
;     ss = wave_sum(ss); ss2 = wave_sum(ss2); const float rs = rsqrtf(ss * (1.0f / 1024.0f) + 1e-6f), rs2 = rsqrtf(ss2 * (1.0f / 1024.0f) + 1e-6f);
;     bf16_t* q = HN + (size_t)row * DM + lane * 8; bf16_t* q2 = HN + (size_t)row2 * DM + lane * 8;
; #pragma unroll
;     for (int i = 0; i < 2; ++i) { store8bf(q + 512 * i, v[2 * i] * rs * gv[2 * i], v[2 * i + 1] * rs * gv[2 * i + 1]); store8bf(q2 + 512 * i, u[2 * i] * rs2 * gv[2 * i], u[2 * i + 1] * rs2 * gv[2 * i + 1]); }
;   }
.LBB0_224:
	v_readfirstlane_b32 s0, v22
	s_nop 3
	s_lshl_b32 s9, s8, 1
	s_add_i32 s11, s0, s8
	s_cmp_lt_i32 s11, s49
	s_cselect_b32 s11, s11, s0
	s_lshl_b32 s12, s0, 12
	s_lshl_b32 s13, s11, 12
	v_mov_b32_e32 v62, s12
	v_mov_b32_e32 v63, 0
	v_lshl_add_u64 v[60:61], v[18:19], 0, v[62:63]
	v_mov_b32_e32 v62, s13
	v_lshl_add_u64 v[64:65], v[18:19], 0, v[62:63]
	global_load_dwordx4 v[26:29], v[60:61], off
	global_load_dwordx4 v[30:33], v[60:61], off offset:16
	global_load_dwordx4 v[34:37], v[60:61], off offset:2048
	global_load_dwordx4 v[38:41], v[60:61], off offset:2064
	global_load_dwordx4 v[42:45], v[64:65], off
	global_load_dwordx4 v[46:49], v[64:65], off offset:16
	global_load_dwordx4 v[50:53], v[64:65], off offset:2048
	global_load_dwordx4 v[54:57], v[64:65], off offset:2064
	s_lshl_b32 s12, s0, 11
	s_lshl_b32 s13, s11, 11
	v_mov_b32_e32 v62, s12
	v_lshl_add_u64 v[24:25], v[20:21], 0, v[62:63]
	v_mov_b32_e32 v62, s13
	v_lshl_add_u64 v[58:59], v[20:21], 0, v[62:63]
	s_add_i32 s1, s0, s9
	s_cmp_lt_i32 s1, s49
	s_cbranch_scc0 .Ln1_lastA_first
	s_add_i32 s11, s1, s8
	s_cmp_lt_i32 s11, s49
	s_cselect_b32 s11, s11, s1
	s_lshl_b32 s12, s1, 12
	s_lshl_b32 s13, s11, 12
	v_mov_b32_e32 v62, s12
	v_mov_b32_e32 v63, 0
	v_lshl_add_u64 v[60:61], v[18:19], 0, v[62:63]
	v_mov_b32_e32 v62, s13
	v_lshl_add_u64 v[64:65], v[18:19], 0, v[62:63]
	global_load_dwordx4 v[72:75], v[60:61], off
	global_load_dwordx4 v[76:79], v[60:61], off offset:16
	global_load_dwordx4 v[80:83], v[60:61], off offset:2048
	global_load_dwordx4 v[88:91], v[60:61], off offset:2064
	global_load_dwordx4 v[92:95], v[64:65], off
	global_load_dwordx4 v[96:99], v[64:65], off offset:16
	global_load_dwordx4 v[100:103], v[64:65], off offset:2048
	global_load_dwordx4 v[128:131], v[64:65], off offset:2064
	s_lshl_b32 s12, s1, 11
	s_lshl_b32 s13, s11, 11
	v_mov_b32_e32 v62, s12
	v_lshl_add_u64 v[132:133], v[20:21], 0, v[62:63]
	v_mov_b32_e32 v62, s13
	v_lshl_add_u64 v[134:135], v[20:21], 0, v[62:63]
	s_waitcnt vmcnt(8)
	v_lshlrev_b32_e32 v0, 2, v210
	v_xor_b32_e32 v0, 0x80, v0
	v_mov_b32_e32 v23, v0
	v_mov_b32_e32 v62, v27
	v_mov_b32_e32 v63, v31
	v_mov_b32_e32 v70, v35
	v_mov_b32_e32 v71, v39
	v_mov_b32_e32 v60, v26
	v_mov_b32_e32 v61, v30
	v_mov_b32_e32 v68, v34
	v_mov_b32_e32 v69, v38
	v_pk_mul_f32 v[62:63], v[62:63], v[62:63]
	v_pk_mul_f32 v[70:71], v[70:71], v[70:71]
	v_pk_fma_f32 v[60:61], v[60:61], v[60:61], v[62:63]
	v_mov_b32_e32 v62, v36
	v_mov_b32_e32 v63, v40
	v_pk_fma_f32 v[68:69], v[68:69], v[68:69], v[70:71]
	v_mov_b32_e32 v64, v28
	v_mov_b32_e32 v65, v32
	v_mov_b32_e32 v70, v37
	v_mov_b32_e32 v71, v41
	v_pk_fma_f32 v[62:63], v[62:63], v[62:63], v[68:69]
	v_mov_b32_e32 v68, v43
	v_mov_b32_e32 v69, v47
	v_mov_b32_e32 v66, v29
	v_mov_b32_e32 v67, v33
	v_pk_fma_f32 v[60:61], v[64:65], v[64:65], v[60:61]
	v_mov_b32_e32 v64, v42
	v_mov_b32_e32 v65, v46
	v_pk_mul_f32 v[68:69], v[68:69], v[68:69]
	v_pk_fma_f32 v[62:63], v[70:71], v[70:71], v[62:63]
	v_mov_b32_e32 v70, v51
	v_mov_b32_e32 v71, v55
	v_pk_fma_f32 v[60:61], v[66:67], v[66:67], v[60:61]
	v_mov_b32_e32 v66, v44
	v_mov_b32_e32 v67, v48
	v_pk_fma_f32 v[64:65], v[64:65], v[64:65], v[68:69]
	v_mov_b32_e32 v68, v50
	v_mov_b32_e32 v69, v54
	v_pk_mul_f32 v[70:71], v[70:71], v[70:71]
	v_pk_fma_f32 v[64:65], v[66:67], v[66:67], v[64:65]
	v_pk_fma_f32 v[68:69], v[68:69], v[68:69], v[70:71]
	v_mov_b32_e32 v70, v45
	v_mov_b32_e32 v71, v49
	v_mov_b32_e32 v66, v52
	v_mov_b32_e32 v67, v56
	v_pk_fma_f32 v[66:67], v[66:67], v[66:67], v[68:69]
	v_mov_b32_e32 v68, v53
	v_mov_b32_e32 v69, v57
	v_pk_fma_f32 v[64:65], v[70:71], v[70:71], v[64:65]
	v_mov_b32_e32 v71, v60
	v_pk_fma_f32 v[66:67], v[68:69], v[68:69], v[66:67]
	v_mov_b32_e32 v70, v64
	v_mov_b32_e32 v60, v65
	v_mov_b32_e32 v69, v62
	v_mov_b32_e32 v68, v66
	v_pk_add_f32 v[60:61], v[70:71], v[60:61]
	v_mov_b32_e32 v62, v67
	v_pk_add_f32 v[60:61], v[60:61], v[68:69]
	s_nop 0
	v_pk_add_f32 v[60:61], v[60:61], v[62:63]
	ds_swizzle_b32 v63, v61 offset:swizzle(SWAP,16)
	ds_swizzle_b32 v62, v60 offset:swizzle(SWAP,16)
	s_waitcnt lgkmcnt(0)
	v_pk_add_f32 v[60:61], v[60:61], v[62:63]
	ds_swizzle_b32 v63, v61 offset:swizzle(SWAP,8)
	ds_swizzle_b32 v62, v60 offset:swizzle(SWAP,8)
	s_waitcnt lgkmcnt(0)
	v_pk_add_f32 v[60:61], v[60:61], v[62:63]
	ds_swizzle_b32 v63, v61 offset:swizzle(SWAP,4)
	ds_swizzle_b32 v62, v60 offset:swizzle(SWAP,4)
	s_waitcnt lgkmcnt(0)
	v_pk_add_f32 v[60:61], v[60:61], v[62:63]
	ds_swizzle_b32 v63, v61 offset:swizzle(SWAP,2)
	ds_swizzle_b32 v62, v60 offset:swizzle(SWAP,2)
	s_waitcnt lgkmcnt(0)
	v_pk_add_f32 v[60:61], v[60:61], v[62:63]
	ds_swizzle_b32 v63, v61 offset:swizzle(SWAP,1)
	ds_swizzle_b32 v62, v60 offset:swizzle(SWAP,1)
	s_waitcnt lgkmcnt(0)
	v_pk_add_f32 v[60:61], v[60:61], v[62:63]
	ds_bpermute_b32 v63, v0, v61
	ds_bpermute_b32 v62, v23, v60
	s_waitcnt lgkmcnt(0)
; __device__ __forceinline__ void store8bf(bf16_t* p, f32x4 v0, f32x4 v1) { u32x4 w; w.x = cvt_pk_bf16(v0[0], v0[1]); w.y = cvt_pk_bf16(v0[2], v0[3]); w.z = cvt_pk_bf16(v1[0], v1[1]); w.w = cvt_pk_bf16(v1[2], v1[3]); *(u32x4*)p = w; }
; template <int M> __device__ __forceinline__ float shx(float v) { return __builtin_bit_cast(float, __builtin_amdgcn_ds_swizzle(__builtin_bit_cast(int, v), (M << 10) | 0x1f)); }
; __device__ __forceinline__ float xhalf(float v) {
;   int l = (int)__builtin_amdgcn_mbcnt_hi(~0u, __builtin_amdgcn_mbcnt_lo(~0u, 0u)); asm volatile("" : "+v"(l));
;   return __builtin_bit_cast(float, __builtin_amdgcn_ds_bpermute((l ^ 32) << 2, __builtin_bit_cast(int, v))); }
; __device__ __forceinline__ float sum32(float v) { return v + xhalf(v); }
; __device__ __forceinline__ float max32(float v) { return __builtin_fmaxf(v, xhalf(v)); }
; __device__ __forceinline__ float wave_sum(float v) {
;   v += shx<16>(v); v += shx<8>(v); v += shx<4>(v); v += shx<2>(v); v += shx<1>(v); return sum32(v);
; }
; __device__ __forceinline__ void norm_phase(const float* H, const float* g, bf16_t* HN) {
;     ...
;   for (int row = gw; row < NREAL + 64; row += 2 * nw) {
;     const int row2 = row + nw < NREAL + 64 ? row + nw : row;
;     const float* p = H + (size_t)row * DM + lane * 8; const float* p2 = H + (size_t)row2 * DM + lane * 8; f32x4 v[4], u[4]; float ss = 0.f, ss2 = 0.f;
; #pragma unroll
;     for (int i = 0; i < 4; ++i) { v[i] = *(const f32x4*)(p + 512 * (i >> 1) + 4 * (i & 1)); u[i] = *(const f32x4*)(p2 + 512 * (i >> 1) + 4 * (i & 1)); }
; #pragma unroll
;     for (int i = 0; i < 4; ++i) { ss += v[i][0] * v[i][0] + v[i][1] * v[i][1] + v[i][2] * v[i][2] + v[i][3] * v[i][3]; ss2 += u[i][0] * u[i][0] + u[i][1] * u[i][1] + u[i][2] * u[i][2] + u[i][3] * u[i][3]; }
;     ss = wave_sum(ss); ss2 = wave_sum(ss2); const float rs = rsqrtf(ss * (1.0f / 1024.0f) + 1e-6f), rs2 = rsqrtf(ss2 * (1.0f / 1024.0f) + 1e-6f);
;     bf16_t* q = HN + (size_t)row * DM + lane * 8; bf16_t* q2 = HN + (size_t)row2 * DM + lane * 8;
; #pragma unroll
;     for (int i = 0; i < 2; ++i) { store8bf(q + 512 * i, v[2 * i] * rs * gv[2 * i], v[2 * i + 1] * rs * gv[2 * i + 1]); store8bf(q2 + 512 * i, u[2 * i] * rs2 * gv[2 * i], u[2 * i + 1] * rs2 * gv[2 * i + 1]); }
;   }
	v_pk_add_f32 v[60:61], v[60:61], v[62:63]
	s_nop 0
	v_pk_fma_f32 v[60:61], v[60:61], s[58:59], v[154:155] op_sel_hi:[1,0,0]
	s_nop 0
	v_mul_f32_e32 v0, 0x4b800000, v61
	v_cmp_gt_f32_e64 s[2:3], s46, v61
	v_mul_f32_e32 v23, 0x4b800000, v60
	v_cmp_gt_f32_e32 vcc, s46, v60
	v_cndmask_b32_e64 v0, v61, v0, s[2:3]
	v_rsq_f32_e32 v0, v0
	v_cndmask_b32_e32 v23, v60, v23, vcc
	v_rsq_f32_e32 v23, v23
	v_mul_f32_e32 v60, 0x45800000, v0
	v_cndmask_b32_e64 v0, v0, v60, s[2:3]
	v_mul_f32_e32 v61, 0x45800000, v23
	v_cndmask_b32_e32 v60, v23, v61, vcc
	v_pk_mul_f32 v[26:27], v[26:27], v[0:1] op_sel_hi:[1,0]
	v_pk_mul_f32 v[28:29], v[28:29], v[0:1] op_sel_hi:[1,0]
	v_pk_mul_f32 v[30:31], v[30:31], v[0:1] op_sel_hi:[1,0]
	v_pk_mul_f32 v[32:33], v[32:33], v[0:1] op_sel_hi:[1,0]
	v_pk_mul_f32 v[42:43], v[42:43], v[60:61] op_sel_hi:[1,0]
	v_pk_mul_f32 v[44:45], v[44:45], v[60:61] op_sel_hi:[1,0]
	v_pk_mul_f32 v[46:47], v[46:47], v[60:61] op_sel_hi:[1,0]
	v_pk_mul_f32 v[48:49], v[48:49], v[60:61] op_sel_hi:[1,0]
	v_pk_mul_f32 v[34:35], v[34:35], v[0:1] op_sel_hi:[1,0]
	v_pk_mul_f32 v[36:37], v[36:37], v[0:1] op_sel_hi:[1,0]
	v_pk_mul_f32 v[38:39], v[38:39], v[0:1] op_sel_hi:[1,0]
	v_pk_mul_f32 v[40:41], v[40:41], v[0:1] op_sel_hi:[1,0]
	v_pk_mul_f32 v[50:51], v[50:51], v[60:61] op_sel_hi:[1,0]
	v_pk_mul_f32 v[52:53], v[52:53], v[60:61] op_sel_hi:[1,0]
	v_pk_mul_f32 v[54:55], v[54:55], v[60:61] op_sel_hi:[1,0]
	v_pk_mul_f32 v[56:57], v[56:57], v[60:61] op_sel_hi:[1,0]
	v_pk_mul_f32 v[28:29], v[8:9], v[28:29]
	v_pk_mul_f32 v[26:27], v[6:7], v[26:27]
	v_pk_mul_f32 v[32:33], v[4:5], v[32:33]
	v_pk_mul_f32 v[30:31], v[2:3], v[30:31]
	v_pk_mul_f32 v[44:45], v[8:9], v[44:45]
	v_pk_mul_f32 v[42:43], v[6:7], v[42:43]
	v_pk_mul_f32 v[48:49], v[4:5], v[48:49]
	v_pk_mul_f32 v[46:47], v[2:3], v[46:47]
	v_pk_mul_f32 v[36:37], v[16:17], v[36:37]
	v_pk_mul_f32 v[34:35], v[14:15], v[34:35]
	v_pk_mul_f32 v[40:41], v[12:13], v[40:41]
	v_pk_mul_f32 v[38:39], v[10:11], v[38:39]
	v_pk_mul_f32 v[52:53], v[16:17], v[52:53]
	v_pk_mul_f32 v[50:51], v[14:15], v[50:51]
	v_pk_mul_f32 v[56:57], v[12:13], v[56:57]
	v_pk_mul_f32 v[54:55], v[10:11], v[54:55]
	v_cvt_pk_bf16_f32 v26, v26, v27
	v_cvt_pk_bf16_f32 v27, v28, v29
	v_cvt_pk_bf16_f32 v28, v30, v31
	v_cvt_pk_bf16_f32 v29, v32, v33
	v_cvt_pk_bf16_f32 v30, v42, v43
	v_cvt_pk_bf16_f32 v31, v44, v45
	v_cvt_pk_bf16_f32 v32, v46, v47
	v_cvt_pk_bf16_f32 v33, v48, v49
	v_cvt_pk_bf16_f32 v34, v34, v35
	v_cvt_pk_bf16_f32 v35, v36, v37
	v_cvt_pk_bf16_f32 v36, v38, v39
	v_cvt_pk_bf16_f32 v37, v40, v41
	v_cvt_pk_bf16_f32 v38, v50, v51
	v_cvt_pk_bf16_f32 v39, v52, v53
	v_cvt_pk_bf16_f32 v40, v54, v55
	v_cvt_pk_bf16_f32 v41, v56, v57
	global_store_dwordx4 v[24:25], v[26:29], off sc1
	global_store_dwordx4 v[58:59], v[30:33], off sc1
	global_store_dwordx4 v[24:25], v[34:37], off offset:1024 sc1
	global_store_dwordx4 v[58:59], v[38:41], off offset:1024 sc1
.Ln1_loop:
	s_add_i32 s0, s1, s9
	s_cmp_lt_i32 s0, s49
	s_cbranch_scc0 .Ln1_lastB
	s_add_i32 s11, s0, s8
	s_cmp_lt_i32 s11, s49
	s_cselect_b32 s11, s11, s0
	s_lshl_b32 s12, s0, 12
	s_lshl_b32 s13, s11, 12
	v_mov_b32_e32 v62, s12
	v_mov_b32_e32 v63, 0
	v_lshl_add_u64 v[60:61], v[18:19], 0, v[62:63]
	v_mov_b32_e32 v62, s13
	v_lshl_add_u64 v[64:65], v[18:19], 0, v[62:63]
	global_load_dwordx4 v[26:29], v[60:61], off
	global_load_dwordx4 v[30:33], v[60:61], off offset:16
	global_load_dwordx4 v[34:37], v[60:61], off offset:2048
	global_load_dwordx4 v[38:41], v[60:61], off offset:2064
	global_load_dwordx4 v[42:45], v[64:65], off
	global_load_dwordx4 v[46:49], v[64:65], off offset:16
	global_load_dwordx4 v[50:53], v[64:65], off offset:2048
	global_load_dwordx4 v[54:57], v[64:65], off offset:2064
	s_lshl_b32 s12, s0, 11
	s_lshl_b32 s13, s11, 11
	v_mov_b32_e32 v62, s12
	v_lshl_add_u64 v[24:25], v[20:21], 0, v[62:63]
	v_mov_b32_e32 v62, s13
	v_lshl_add_u64 v[58:59], v[20:21], 0, v[62:63]
	s_waitcnt vmcnt(12)
	v_lshlrev_b32_e32 v0, 2, v210
	v_xor_b32_e32 v0, 0x80, v0
	v_mov_b32_e32 v23, v0
	v_mov_b32_e32 v62, v73
	v_mov_b32_e32 v63, v77
	v_mov_b32_e32 v70, v81
	v_mov_b32_e32 v71, v89
	v_mov_b32_e32 v60, v72
	v_mov_b32_e32 v61, v76
	v_mov_b32_e32 v68, v80
	v_mov_b32_e32 v69, v88
	v_pk_mul_f32 v[62:63], v[62:63], v[62:63]
	v_pk_mul_f32 v[70:71], v[70:71], v[70:71]
	v_pk_fma_f32 v[60:61], v[60:61], v[60:61], v[62:63]
	v_mov_b32_e32 v62, v82
	v_mov_b32_e32 v63, v90
	v_pk_fma_f32 v[68:69], v[68:69], v[68:69], v[70:71]
	v_mov_b32_e32 v64, v74
	v_mov_b32_e32 v65, v78
	v_mov_b32_e32 v70, v83
	v_mov_b32_e32 v71, v91
	v_pk_fma_f32 v[62:63], v[62:63], v[62:63], v[68:69]
	v_mov_b32_e32 v68, v93
	v_mov_b32_e32 v69, v97
	v_mov_b32_e32 v66, v75
	v_mov_b32_e32 v67, v79
	v_pk_fma_f32 v[60:61], v[64:65], v[64:65], v[60:61]
	v_mov_b32_e32 v64, v92
	v_mov_b32_e32 v65, v96
	v_pk_mul_f32 v[68:69], v[68:69], v[68:69]
	v_pk_fma_f32 v[62:63], v[70:71], v[70:71], v[62:63]
	v_mov_b32_e32 v70, v101
	v_mov_b32_e32 v71, v129
	v_pk_fma_f32 v[60:61], v[66:67], v[66:67], v[60:61]
	v_mov_b32_e32 v66, v94
	v_mov_b32_e32 v67, v98
	v_pk_fma_f32 v[64:65], v[64:65], v[64:65], v[68:69]
	v_mov_b32_e32 v68, v100
	v_mov_b32_e32 v69, v128
	v_pk_mul_f32 v[70:71], v[70:71], v[70:71]
	v_pk_fma_f32 v[64:65], v[66:67], v[66:67], v[64:65]
	v_pk_fma_f32 v[68:69], v[68:69], v[68:69], v[70:71]
	v_mov_b32_e32 v70, v95
	v_mov_b32_e32 v71, v99
	v_mov_b32_e32 v66, v102
	v_mov_b32_e32 v67, v130
	v_pk_fma_f32 v[66:67], v[66:67], v[66:67], v[68:69]
	v_mov_b32_e32 v68, v103
	v_mov_b32_e32 v69, v131
	v_pk_fma_f32 v[64:65], v[70:71], v[70:71], v[64:65]
	v_mov_b32_e32 v71, v60
	v_pk_fma_f32 v[66:67], v[68:69], v[68:69], v[66:67]
	v_mov_b32_e32 v70, v64
	v_mov_b32_e32 v60, v65
	v_mov_b32_e32 v69, v62
	v_mov_b32_e32 v68, v66
	v_pk_add_f32 v[60:61], v[70:71], v[60:61]
	v_mov_b32_e32 v62, v67
	v_pk_add_f32 v[60:61], v[60:61], v[68:69]
	s_nop 0
	v_pk_add_f32 v[60:61], v[60:61], v[62:63]
	ds_swizzle_b32 v63, v61 offset:swizzle(SWAP,16)
	ds_swizzle_b32 v62, v60 offset:swizzle(SWAP,16)
	s_waitcnt lgkmcnt(0)
; __device__ __forceinline__ void store8bf(bf16_t* p, f32x4 v0, f32x4 v1) { u32x4 w; w.x = cvt_pk_bf16(v0[0], v0[1]); w.y = cvt_pk_bf16(v0[2], v0[3]); w.z = cvt_pk_bf16(v1[0], v1[1]); w.w = cvt_pk_bf16(v1[2], v1[3]); *(u32x4*)p = w; }
; template <int M> __device__ __forceinline__ float shx(float v) { return __builtin_bit_cast(float, __builtin_amdgcn_ds_swizzle(__builtin_bit_cast(int, v), (M << 10) | 0x1f)); }
; __device__ __forceinline__ float xhalf(float v) {
;   int l = (int)__builtin_amdgcn_mbcnt_hi(~0u, __builtin_amdgcn_mbcnt_lo(~0u, 0u)); asm volatile("" : "+v"(l));
;   return __builtin_bit_cast(float, __builtin_amdgcn_ds_bpermute((l ^ 32) << 2, __builtin_bit_cast(int, v))); }
; __device__ __forceinline__ float sum32(float v) { return v + xhalf(v); }
; __device__ __forceinline__ float max32(float v) { return __builtin_fmaxf(v, xhalf(v)); }
; __device__ __forceinline__ float wave_sum(float v) {
;   v += shx<16>(v); v += shx<8>(v); v += shx<4>(v); v += shx<2>(v); v += shx<1>(v); return sum32(v);
; }
; __device__ __forceinline__ void norm_phase(const float* H, const float* g, bf16_t* HN) {
;     ...
;   for (int row = gw; row < NREAL + 64; row += 2 * nw) {
;     const int row2 = row + nw < NREAL + 64 ? row + nw : row;
;     const float* p = H + (size_t)row * DM + lane * 8; const float* p2 = H + (size_t)row2 * DM + lane * 8; f32x4 v[4], u[4]; float ss = 0.f, ss2 = 0.f;
; #pragma unroll
;     for (int i = 0; i < 4; ++i) { v[i] = *(const f32x4*)(p + 512 * (i >> 1) + 4 * (i & 1)); u[i] = *(const f32x4*)(p2 + 512 * (i >> 1) + 4 * (i & 1)); }
; #pragma unroll
;     for (int i = 0; i < 4; ++i) { ss += v[i][0] * v[i][0] + v[i][1] * v[i][1] + v[i][2] * v[i][2] + v[i][3] * v[i][3]; ss2 += u[i][0] * u[i][0] + u[i][1] * u[i][1] + u[i][2] * u[i][2] + u[i][3] * u[i][3]; }
;     ss = wave_sum(ss); ss2 = wave_sum(ss2); const float rs = rsqrtf(ss * (1.0f / 1024.0f) + 1e-6f), rs2 = rsqrtf(ss2 * (1.0f / 1024.0f) + 1e-6f);
;     bf16_t* q = HN + (size_t)row * DM + lane * 8; bf16_t* q2 = HN + (size_t)row2 * DM + lane * 8;
; #pragma unroll
;     for (int i = 0; i < 2; ++i) { store8bf(q + 512 * i, v[2 * i] * rs * gv[2 * i], v[2 * i + 1] * rs * gv[2 * i + 1]); store8bf(q2 + 512 * i, u[2 * i] * rs2 * gv[2 * i], u[2 * i + 1] * rs2 * gv[2 * i + 1]); }
;   }
	v_pk_add_f32 v[60:61], v[60:61], v[62:63]
	ds_swizzle_b32 v63, v61 offset:swizzle(SWAP,8)
	ds_swizzle_b32 v62, v60 offset:swizzle(SWAP,8)
	s_waitcnt lgkmcnt(0)
	v_pk_add_f32 v[60:61], v[60:61], v[62:63]
	ds_swizzle_b32 v63, v61 offset:swizzle(SWAP,4)
	ds_swizzle_b32 v62, v60 offset:swizzle(SWAP,4)
	s_waitcnt lgkmcnt(0)
	v_pk_add_f32 v[60:61], v[60:61], v[62:63]
	ds_swizzle_b32 v63, v61 offset:swizzle(SWAP,2)
	ds_swizzle_b32 v62, v60 offset:swizzle(SWAP,2)
	s_waitcnt lgkmcnt(0)
	v_pk_add_f32 v[60:61], v[60:61], v[62:63]
	ds_swizzle_b32 v63, v61 offset:swizzle(SWAP,1)
	ds_swizzle_b32 v62, v60 offset:swizzle(SWAP,1)
	s_waitcnt lgkmcnt(0)
	v_pk_add_f32 v[60:61], v[60:61], v[62:63]
	ds_bpermute_b32 v63, v0, v61
	ds_bpermute_b32 v62, v23, v60
	s_waitcnt lgkmcnt(0)
	v_pk_add_f32 v[60:61], v[60:61], v[62:63]
	s_nop 0
	v_pk_fma_f32 v[60:61], v[60:61], s[58:59], v[154:155] op_sel_hi:[1,0,0]
	s_nop 0
	v_mul_f32_e32 v0, 0x4b800000, v61
	v_cmp_gt_f32_e64 s[2:3], s46, v61
	v_mul_f32_e32 v23, 0x4b800000, v60
	v_cmp_gt_f32_e32 vcc, s46, v60
	v_cndmask_b32_e64 v0, v61, v0, s[2:3]
	v_rsq_f32_e32 v0, v0
	v_cndmask_b32_e32 v23, v60, v23, vcc
	v_rsq_f32_e32 v23, v23
	v_mul_f32_e32 v60, 0x45800000, v0
	v_cndmask_b32_e64 v0, v0, v60, s[2:3]
	v_mul_f32_e32 v61, 0x45800000, v23
	v_cndmask_b32_e32 v60, v23, v61, vcc
	v_pk_mul_f32 v[72:73], v[72:73], v[0:1] op_sel_hi:[1,0]
	v_pk_mul_f32 v[74:75], v[74:75], v[0:1] op_sel_hi:[1,0]
	v_pk_mul_f32 v[76:77], v[76:77], v[0:1] op_sel_hi:[1,0]
	v_pk_mul_f32 v[78:79], v[78:79], v[0:1] op_sel_hi:[1,0]
	v_pk_mul_f32 v[92:93], v[92:93], v[60:61] op_sel_hi:[1,0]
	v_pk_mul_f32 v[94:95], v[94:95], v[60:61] op_sel_hi:[1,0]
	v_pk_mul_f32 v[96:97], v[96:97], v[60:61] op_sel_hi:[1,0]
	v_pk_mul_f32 v[98:99], v[98:99], v[60:61] op_sel_hi:[1,0]
	v_pk_mul_f32 v[80:81], v[80:81], v[0:1] op_sel_hi:[1,0]
	v_pk_mul_f32 v[82:83], v[82:83], v[0:1] op_sel_hi:[1,0]
	v_pk_mul_f32 v[88:89], v[88:89], v[0:1] op_sel_hi:[1,0]
	v_pk_mul_f32 v[90:91], v[90:91], v[0:1] op_sel_hi:[1,0]
	v_pk_mul_f32 v[100:101], v[100:101], v[60:61] op_sel_hi:[1,0]
	v_pk_mul_f32 v[102:103], v[102:103], v[60:61] op_sel_hi:[1,0]
	v_pk_mul_f32 v[128:129], v[128:129], v[60:61] op_sel_hi:[1,0]
	v_pk_mul_f32 v[130:131], v[130:131], v[60:61] op_sel_hi:[1,0]
	v_pk_mul_f32 v[74:75], v[8:9], v[74:75]
	v_pk_mul_f32 v[72:73], v[6:7], v[72:73]
	v_pk_mul_f32 v[78:79], v[4:5], v[78:79]
	v_pk_mul_f32 v[76:77], v[2:3], v[76:77]
	v_pk_mul_f32 v[94:95], v[8:9], v[94:95]
	v_pk_mul_f32 v[92:93], v[6:7], v[92:93]
	v_pk_mul_f32 v[98:99], v[4:5], v[98:99]
	v_pk_mul_f32 v[96:97], v[2:3], v[96:97]
	v_pk_mul_f32 v[82:83], v[16:17], v[82:83]
	v_pk_mul_f32 v[80:81], v[14:15], v[80:81]
	v_pk_mul_f32 v[90:91], v[12:13], v[90:91]
	v_pk_mul_f32 v[88:89], v[10:11], v[88:89]
	v_pk_mul_f32 v[102:103], v[16:17], v[102:103]
	v_pk_mul_f32 v[100:101], v[14:15], v[100:101]
	v_pk_mul_f32 v[130:131], v[12:13], v[130:131]
	v_pk_mul_f32 v[128:129], v[10:11], v[128:129]
	v_cvt_pk_bf16_f32 v72, v72, v73
	v_cvt_pk_bf16_f32 v73, v74, v75
	v_cvt_pk_bf16_f32 v74, v76, v77
	v_cvt_pk_bf16_f32 v75, v78, v79
	v_cvt_pk_bf16_f32 v76, v92, v93
	v_cvt_pk_bf16_f32 v77, v94, v95
	v_cvt_pk_bf16_f32 v78, v96, v97
	v_cvt_pk_bf16_f32 v79, v98, v99
	v_cvt_pk_bf16_f32 v80, v80, v81
	v_cvt_pk_bf16_f32 v81, v82, v83
	v_cvt_pk_bf16_f32 v82, v88, v89
	v_cvt_pk_bf16_f32 v83, v90, v91
	v_cvt_pk_bf16_f32 v88, v100, v101
	v_cvt_pk_bf16_f32 v89, v102, v103
	v_cvt_pk_bf16_f32 v90, v128, v129
	v_cvt_pk_bf16_f32 v91, v130, v131
	global_store_dwordx4 v[132:133], v[72:75], off sc1
	global_store_dwordx4 v[134:135], v[76:79], off sc1
	global_store_dwordx4 v[132:133], v[80:83], off offset:1024 sc1
	global_store_dwordx4 v[134:135], v[88:91], off offset:1024 sc1
	s_add_i32 s1, s0, s9
	s_cmp_lt_i32 s1, s49
	s_cbranch_scc0 .Ln1_lastA
	s_add_i32 s11, s1, s8
	s_cmp_lt_i32 s11, s49
	s_cselect_b32 s11, s11, s1
	s_lshl_b32 s12, s1, 12
	s_lshl_b32 s13, s11, 12
	v_mov_b32_e32 v62, s12
	v_mov_b32_e32 v63, 0
	v_lshl_add_u64 v[60:61], v[18:19], 0, v[62:63]
	v_mov_b32_e32 v62, s13
	v_lshl_add_u64 v[64:65], v[18:19], 0, v[62:63]
	global_load_dwordx4 v[72:75], v[60:61], off
	global_load_dwordx4 v[76:79], v[60:61], off offset:16
	global_load_dwordx4 v[80:83], v[60:61], off offset:2048
	global_load_dwordx4 v[88:91], v[60:61], off offset:2064
	global_load_dwordx4 v[92:95], v[64:65], off
	global_load_dwordx4 v[96:99], v[64:65], off offset:16
	global_load_dwordx4 v[100:103], v[64:65], off offset:2048
	global_load_dwordx4 v[128:131], v[64:65], off offset:2064
	s_lshl_b32 s12, s1, 11
	s_lshl_b32 s13, s11, 11
	v_mov_b32_e32 v62, s12
	v_lshl_add_u64 v[132:133], v[20:21], 0, v[62:63]
	v_mov_b32_e32 v62, s13
	v_lshl_add_u64 v[134:135], v[20:21], 0, v[62:63]
	s_waitcnt vmcnt(12)
; __device__ __forceinline__ void store8bf(bf16_t* p, f32x4 v0, f32x4 v1) { u32x4 w; w.x = cvt_pk_bf16(v0[0], v0[1]); w.y = cvt_pk_bf16(v0[2], v0[3]); w.z = cvt_pk_bf16(v1[0], v1[1]); w.w = cvt_pk_bf16(v1[2], v1[3]); *(u32x4*)p = w; }
; template <int M> __device__ __forceinline__ float shx(float v) { return __builtin_bit_cast(float, __builtin_amdgcn_ds_swizzle(__builtin_bit_cast(int, v), (M << 10) | 0x1f)); }
; __device__ __forceinline__ float xhalf(float v) {
;   int l = (int)__builtin_amdgcn_mbcnt_hi(~0u, __builtin_amdgcn_mbcnt_lo(~0u, 0u)); asm volatile("" : "+v"(l));
;   return __builtin_bit_cast(float, __builtin_amdgcn_ds_bpermute((l ^ 32) << 2, __builtin_bit_cast(int, v))); }
; __device__ __forceinline__ float sum32(float v) { return v + xhalf(v); }
; __device__ __forceinline__ float max32(float v) { return __builtin_fmaxf(v, xhalf(v)); }
; __device__ __forceinline__ float wave_sum(float v) {
;   v += shx<16>(v); v += shx<8>(v); v += shx<4>(v); v += shx<2>(v); v += shx<1>(v); return sum32(v);
; }
; __device__ __forceinline__ void norm_phase(const float* H, const float* g, bf16_t* HN) {
;     ...
;   for (int row = gw; row < NREAL + 64; row += 2 * nw) {
;     const int row2 = row + nw < NREAL + 64 ? row + nw : row;
;     const float* p = H + (size_t)row * DM + lane * 8; const float* p2 = H + (size_t)row2 * DM + lane * 8; f32x4 v[4], u[4]; float ss = 0.f, ss2 = 0.f;
; #pragma unroll
;     for (int i = 0; i < 4; ++i) { v[i] = *(const f32x4*)(p + 512 * (i >> 1) + 4 * (i & 1)); u[i] = *(const f32x4*)(p2 + 512 * (i >> 1) + 4 * (i & 1)); }
; #pragma unroll
;     for (int i = 0; i < 4; ++i) { ss += v[i][0] * v[i][0] + v[i][1] * v[i][1] + v[i][2] * v[i][2] + v[i][3] * v[i][3]; ss2 += u[i][0] * u[i][0] + u[i][1] * u[i][1] + u[i][2] * u[i][2] + u[i][3] * u[i][3]; }
;     ss = wave_sum(ss); ss2 = wave_sum(ss2); const float rs = rsqrtf(ss * (1.0f / 1024.0f) + 1e-6f), rs2 = rsqrtf(ss2 * (1.0f / 1024.0f) + 1e-6f);
;     bf16_t* q = HN + (size_t)row * DM + lane * 8; bf16_t* q2 = HN + (size_t)row2 * DM + lane * 8;
; #pragma unroll
;     for (int i = 0; i < 2; ++i) { store8bf(q + 512 * i, v[2 * i] * rs * gv[2 * i], v[2 * i + 1] * rs * gv[2 * i + 1]); store8bf(q2 + 512 * i, u[2 * i] * rs2 * gv[2 * i], u[2 * i + 1] * rs2 * gv[2 * i + 1]); }
;   }
	v_lshlrev_b32_e32 v0, 2, v210
	v_xor_b32_e32 v0, 0x80, v0
	v_mov_b32_e32 v23, v0
	v_mov_b32_e32 v62, v27
	v_mov_b32_e32 v63, v31
	v_mov_b32_e32 v70, v35
	v_mov_b32_e32 v71, v39
	v_mov_b32_e32 v60, v26
	v_mov_b32_e32 v61, v30
	v_mov_b32_e32 v68, v34
	v_mov_b32_e32 v69, v38
	v_pk_mul_f32 v[62:63], v[62:63], v[62:63]
	v_pk_mul_f32 v[70:71], v[70:71], v[70:71]
	v_pk_fma_f32 v[60:61], v[60:61], v[60:61], v[62:63]
	v_mov_b32_e32 v62, v36
	v_mov_b32_e32 v63, v40
	v_pk_fma_f32 v[68:69], v[68:69], v[68:69], v[70:71]
	v_mov_b32_e32 v64, v28
	v_mov_b32_e32 v65, v32
	v_mov_b32_e32 v70, v37
	v_mov_b32_e32 v71, v41
	v_pk_fma_f32 v[62:63], v[62:63], v[62:63], v[68:69]
	v_mov_b32_e32 v68, v43
	v_mov_b32_e32 v69, v47
	v_mov_b32_e32 v66, v29
	v_mov_b32_e32 v67, v33
	v_pk_fma_f32 v[60:61], v[64:65], v[64:65], v[60:61]
	v_mov_b32_e32 v64, v42
	v_mov_b32_e32 v65, v46
	v_pk_mul_f32 v[68:69], v[68:69], v[68:69]
	v_pk_fma_f32 v[62:63], v[70:71], v[70:71], v[62:63]
	v_mov_b32_e32 v70, v51
	v_mov_b32_e32 v71, v55
	v_pk_fma_f32 v[60:61], v[66:67], v[66:67], v[60:61]
	v_mov_b32_e32 v66, v44
	v_mov_b32_e32 v67, v48
	v_pk_fma_f32 v[64:65], v[64:65], v[64:65], v[68:69]
	v_mov_b32_e32 v68, v50
	v_mov_b32_e32 v69, v54
	v_pk_mul_f32 v[70:71], v[70:71], v[70:71]
	v_pk_fma_f32 v[64:65], v[66:67], v[66:67], v[64:65]
	v_pk_fma_f32 v[68:69], v[68:69], v[68:69], v[70:71]
	v_mov_b32_e32 v70, v45
	v_mov_b32_e32 v71, v49
	v_mov_b32_e32 v66, v52
	v_mov_b32_e32 v67, v56
	v_pk_fma_f32 v[66:67], v[66:67], v[66:67], v[68:69]
	v_mov_b32_e32 v68, v53
	v_mov_b32_e32 v69, v57
	v_pk_fma_f32 v[64:65], v[70:71], v[70:71], v[64:65]
	v_mov_b32_e32 v71, v60
	v_pk_fma_f32 v[66:67], v[68:69], v[68:69], v[66:67]
	v_mov_b32_e32 v70, v64
	v_mov_b32_e32 v60, v65
	v_mov_b32_e32 v69, v62
	v_mov_b32_e32 v68, v66
	v_pk_add_f32 v[60:61], v[70:71], v[60:61]
	v_mov_b32_e32 v62, v67
	v_pk_add_f32 v[60:61], v[60:61], v[68:69]
	s_nop 0
	v_pk_add_f32 v[60:61], v[60:61], v[62:63]
	ds_swizzle_b32 v63, v61 offset:swizzle(SWAP,16)
	ds_swizzle_b32 v62, v60 offset:swizzle(SWAP,16)
	s_waitcnt lgkmcnt(0)
	v_pk_add_f32 v[60:61], v[60:61], v[62:63]
	ds_swizzle_b32 v63, v61 offset:swizzle(SWAP,8)
	ds_swizzle_b32 v62, v60 offset:swizzle(SWAP,8)
	s_waitcnt lgkmcnt(0)
	v_pk_add_f32 v[60:61], v[60:61], v[62:63]
	ds_swizzle_b32 v63, v61 offset:swizzle(SWAP,4)
	ds_swizzle_b32 v62, v60 offset:swizzle(SWAP,4)
	s_waitcnt lgkmcnt(0)
	v_pk_add_f32 v[60:61], v[60:61], v[62:63]
	ds_swizzle_b32 v63, v61 offset:swizzle(SWAP,2)
	ds_swizzle_b32 v62, v60 offset:swizzle(SWAP,2)
	s_waitcnt lgkmcnt(0)
	v_pk_add_f32 v[60:61], v[60:61], v[62:63]
	ds_swizzle_b32 v63, v61 offset:swizzle(SWAP,1)
	ds_swizzle_b32 v62, v60 offset:swizzle(SWAP,1)
	s_waitcnt lgkmcnt(0)
	v_pk_add_f32 v[60:61], v[60:61], v[62:63]
	ds_bpermute_b32 v63, v0, v61
	ds_bpermute_b32 v62, v23, v60
	s_waitcnt lgkmcnt(0)
	v_pk_add_f32 v[60:61], v[60:61], v[62:63]
	s_nop 0
	v_pk_fma_f32 v[60:61], v[60:61], s[58:59], v[154:155] op_sel_hi:[1,0,0]
	s_nop 0
	v_mul_f32_e32 v0, 0x4b800000, v61
	v_cmp_gt_f32_e64 s[2:3], s46, v61
	v_mul_f32_e32 v23, 0x4b800000, v60
	v_cmp_gt_f32_e32 vcc, s46, v60
	v_cndmask_b32_e64 v0, v61, v0, s[2:3]
	v_rsq_f32_e32 v0, v0
	v_cndmask_b32_e32 v23, v60, v23, vcc
	v_rsq_f32_e32 v23, v23
	v_mul_f32_e32 v60, 0x45800000, v0
	v_cndmask_b32_e64 v0, v0, v60, s[2:3]
	v_mul_f32_e32 v61, 0x45800000, v23
	v_cndmask_b32_e32 v60, v23, v61, vcc
	v_pk_mul_f32 v[26:27], v[26:27], v[0:1] op_sel_hi:[1,0]
	v_pk_mul_f32 v[28:29], v[28:29], v[0:1] op_sel_hi:[1,0]
	v_pk_mul_f32 v[30:31], v[30:31], v[0:1] op_sel_hi:[1,0]
	v_pk_mul_f32 v[32:33], v[32:33], v[0:1] op_sel_hi:[1,0]
	v_pk_mul_f32 v[42:43], v[42:43], v[60:61] op_sel_hi:[1,0]
	v_pk_mul_f32 v[44:45], v[44:45], v[60:61] op_sel_hi:[1,0]
	v_pk_mul_f32 v[46:47], v[46:47], v[60:61] op_sel_hi:[1,0]
	v_pk_mul_f32 v[48:49], v[48:49], v[60:61] op_sel_hi:[1,0]
	v_pk_mul_f32 v[34:35], v[34:35], v[0:1] op_sel_hi:[1,0]
	v_pk_mul_f32 v[36:37], v[36:37], v[0:1] op_sel_hi:[1,0]
	v_pk_mul_f32 v[38:39], v[38:39], v[0:1] op_sel_hi:[1,0]
	v_pk_mul_f32 v[40:41], v[40:41], v[0:1] op_sel_hi:[1,0]
	v_pk_mul_f32 v[50:51], v[50:51], v[60:61] op_sel_hi:[1,0]
	v_pk_mul_f32 v[52:53], v[52:53], v[60:61] op_sel_hi:[1,0]
	v_pk_mul_f32 v[54:55], v[54:55], v[60:61] op_sel_hi:[1,0]
	v_pk_mul_f32 v[56:57], v[56:57], v[60:61] op_sel_hi:[1,0]
	v_pk_mul_f32 v[28:29], v[8:9], v[28:29]
	v_pk_mul_f32 v[26:27], v[6:7], v[26:27]
	v_pk_mul_f32 v[32:33], v[4:5], v[32:33]
	v_pk_mul_f32 v[30:31], v[2:3], v[30:31]
	v_pk_mul_f32 v[44:45], v[8:9], v[44:45]
	v_pk_mul_f32 v[42:43], v[6:7], v[42:43]
	v_pk_mul_f32 v[48:49], v[4:5], v[48:49]
	v_pk_mul_f32 v[46:47], v[2:3], v[46:47]
	v_pk_mul_f32 v[36:37], v[16:17], v[36:37]
	v_pk_mul_f32 v[34:35], v[14:15], v[34:35]
	v_pk_mul_f32 v[40:41], v[12:13], v[40:41]
	v_pk_mul_f32 v[38:39], v[10:11], v[38:39]
	v_pk_mul_f32 v[52:53], v[16:17], v[52:53]
	v_pk_mul_f32 v[50:51], v[14:15], v[50:51]
	v_pk_mul_f32 v[56:57], v[12:13], v[56:57]
	v_pk_mul_f32 v[54:55], v[10:11], v[54:55]
	v_cvt_pk_bf16_f32 v26, v26, v27
	v_cvt_pk_bf16_f32 v27, v28, v29
	v_cvt_pk_bf16_f32 v28, v30, v31
	v_cvt_pk_bf16_f32 v29, v32, v33
	v_cvt_pk_bf16_f32 v30, v42, v43
	v_cvt_pk_bf16_f32 v31, v44, v45
	v_cvt_pk_bf16_f32 v32, v46, v47
	v_cvt_pk_bf16_f32 v33, v48, v49
	v_cvt_pk_bf16_f32 v34, v34, v35
	v_cvt_pk_bf16_f32 v35, v36, v37
	v_cvt_pk_bf16_f32 v36, v38, v39
	v_cvt_pk_bf16_f32 v37, v40, v41
	v_cvt_pk_bf16_f32 v38, v50, v51
	v_cvt_pk_bf16_f32 v39, v52, v53
	v_cvt_pk_bf16_f32 v40, v54, v55
	v_cvt_pk_bf16_f32 v41, v56, v57
	global_store_dwordx4 v[24:25], v[26:29], off sc1
	global_store_dwordx4 v[58:59], v[30:33], off sc1
	global_store_dwordx4 v[24:25], v[34:37], off offset:1024 sc1
	global_store_dwordx4 v[58:59], v[38:41], off offset:1024 sc1
	s_branch .Ln1_loop
; __device__ __forceinline__ void store8bf(bf16_t* p, f32x4 v0, f32x4 v1) { u32x4 w; w.x = cvt_pk_bf16(v0[0], v0[1]); w.y = cvt_pk_bf16(v0[2], v0[3]); w.z = cvt_pk_bf16(v1[0], v1[1]); w.w = cvt_pk_bf16(v1[2], v1[3]); *(u32x4*)p = w; }
; template <int M> __device__ __forceinline__ float shx(float v) { return __builtin_bit_cast(float, __builtin_amdgcn_ds_swizzle(__builtin_bit_cast(int, v), (M << 10) | 0x1f)); }
; __device__ __forceinline__ float xhalf(float v) {
;   int l = (int)__builtin_amdgcn_mbcnt_hi(~0u, __builtin_amdgcn_mbcnt_lo(~0u, 0u)); asm volatile("" : "+v"(l));
;   return __builtin_bit_cast(float, __builtin_amdgcn_ds_bpermute((l ^ 32) << 2, __builtin_bit_cast(int, v))); }
; __device__ __forceinline__ float sum32(float v) { return v + xhalf(v); }
; __device__ __forceinline__ float max32(float v) { return __builtin_fmaxf(v, xhalf(v)); }
; __device__ __forceinline__ float wave_sum(float v) {
;   v += shx<16>(v); v += shx<8>(v); v += shx<4>(v); v += shx<2>(v); v += shx<1>(v); return sum32(v);
; }
; __device__ __forceinline__ void norm_phase(const float* H, const float* g, bf16_t* HN) {
;     ...
;   for (int row = gw; row < NREAL + 64; row += 2 * nw) {
;     const int row2 = row + nw < NREAL + 64 ? row + nw : row;
;     const float* p = H + (size_t)row * DM + lane * 8; const float* p2 = H + (size_t)row2 * DM + lane * 8; f32x4 v[4], u[4]; float ss = 0.f, ss2 = 0.f;
; #pragma unroll
;     for (int i = 0; i < 4; ++i) { v[i] = *(const f32x4*)(p + 512 * (i >> 1) + 4 * (i & 1)); u[i] = *(const f32x4*)(p2 + 512 * (i >> 1) + 4 * (i & 1)); }
; #pragma unroll
;     for (int i = 0; i < 4; ++i) { ss += v[i][0] * v[i][0] + v[i][1] * v[i][1] + v[i][2] * v[i][2] + v[i][3] * v[i][3]; ss2 += u[i][0] * u[i][0] + u[i][1] * u[i][1] + u[i][2] * u[i][2] + u[i][3] * u[i][3]; }
;     ss = wave_sum(ss); ss2 = wave_sum(ss2); const float rs = rsqrtf(ss * (1.0f / 1024.0f) + 1e-6f), rs2 = rsqrtf(ss2 * (1.0f / 1024.0f) + 1e-6f);
;     bf16_t* q = HN + (size_t)row * DM + lane * 8; bf16_t* q2 = HN + (size_t)row2 * DM + lane * 8;
; #pragma unroll
;     for (int i = 0; i < 2; ++i) { store8bf(q + 512 * i, v[2 * i] * rs * gv[2 * i], v[2 * i + 1] * rs * gv[2 * i + 1]); store8bf(q2 + 512 * i, u[2 * i] * rs2 * gv[2 * i], u[2 * i + 1] * rs2 * gv[2 * i + 1]); }
;   }
.Ln1_lastA_first:
	s_waitcnt vmcnt(0)
	v_lshlrev_b32_e32 v0, 2, v210
	v_xor_b32_e32 v0, 0x80, v0
	v_mov_b32_e32 v23, v0
	v_mov_b32_e32 v62, v27
	v_mov_b32_e32 v63, v31
	v_mov_b32_e32 v70, v35
	v_mov_b32_e32 v71, v39
	v_mov_b32_e32 v60, v26
	v_mov_b32_e32 v61, v30
	v_mov_b32_e32 v68, v34
	v_mov_b32_e32 v69, v38
	v_pk_mul_f32 v[62:63], v[62:63], v[62:63]
	v_pk_mul_f32 v[70:71], v[70:71], v[70:71]
	v_pk_fma_f32 v[60:61], v[60:61], v[60:61], v[62:63]
	v_mov_b32_e32 v62, v36
	v_mov_b32_e32 v63, v40
	v_pk_fma_f32 v[68:69], v[68:69], v[68:69], v[70:71]
	v_mov_b32_e32 v64, v28
	v_mov_b32_e32 v65, v32
	v_mov_b32_e32 v70, v37
	v_mov_b32_e32 v71, v41
	v_pk_fma_f32 v[62:63], v[62:63], v[62:63], v[68:69]
	v_mov_b32_e32 v68, v43
	v_mov_b32_e32 v69, v47
	v_mov_b32_e32 v66, v29
	v_mov_b32_e32 v67, v33
	v_pk_fma_f32 v[60:61], v[64:65], v[64:65], v[60:61]
	v_mov_b32_e32 v64, v42
	v_mov_b32_e32 v65, v46
	v_pk_mul_f32 v[68:69], v[68:69], v[68:69]
	v_pk_fma_f32 v[62:63], v[70:71], v[70:71], v[62:63]
	v_mov_b32_e32 v70, v51
	v_mov_b32_e32 v71, v55
	v_pk_fma_f32 v[60:61], v[66:67], v[66:67], v[60:61]
	v_mov_b32_e32 v66, v44
	v_mov_b32_e32 v67, v48
	v_pk_fma_f32 v[64:65], v[64:65], v[64:65], v[68:69]
	v_mov_b32_e32 v68, v50
	v_mov_b32_e32 v69, v54
	v_pk_mul_f32 v[70:71], v[70:71], v[70:71]
	v_pk_fma_f32 v[64:65], v[66:67], v[66:67], v[64:65]
	v_pk_fma_f32 v[68:69], v[68:69], v[68:69], v[70:71]
	v_mov_b32_e32 v70, v45
	v_mov_b32_e32 v71, v49
	v_mov_b32_e32 v66, v52
	v_mov_b32_e32 v67, v56
	v_pk_fma_f32 v[66:67], v[66:67], v[66:67], v[68:69]
	v_mov_b32_e32 v68, v53
	v_mov_b32_e32 v69, v57
	v_pk_fma_f32 v[64:65], v[70:71], v[70:71], v[64:65]
	v_mov_b32_e32 v71, v60
	v_pk_fma_f32 v[66:67], v[68:69], v[68:69], v[66:67]
	v_mov_b32_e32 v70, v64
	v_mov_b32_e32 v60, v65
	v_mov_b32_e32 v69, v62
	v_mov_b32_e32 v68, v66
	v_pk_add_f32 v[60:61], v[70:71], v[60:61]
	v_mov_b32_e32 v62, v67
	v_pk_add_f32 v[60:61], v[60:61], v[68:69]
	s_nop 0
	v_pk_add_f32 v[60:61], v[60:61], v[62:63]
	ds_swizzle_b32 v63, v61 offset:swizzle(SWAP,16)
	ds_swizzle_b32 v62, v60 offset:swizzle(SWAP,16)
	s_waitcnt lgkmcnt(0)
	v_pk_add_f32 v[60:61], v[60:61], v[62:63]
	ds_swizzle_b32 v63, v61 offset:swizzle(SWAP,8)
	ds_swizzle_b32 v62, v60 offset:swizzle(SWAP,8)
	s_waitcnt lgkmcnt(0)
	v_pk_add_f32 v[60:61], v[60:61], v[62:63]
	ds_swizzle_b32 v63, v61 offset:swizzle(SWAP,4)
	ds_swizzle_b32 v62, v60 offset:swizzle(SWAP,4)
	s_waitcnt lgkmcnt(0)
	v_pk_add_f32 v[60:61], v[60:61], v[62:63]
	ds_swizzle_b32 v63, v61 offset:swizzle(SWAP,2)
	ds_swizzle_b32 v62, v60 offset:swizzle(SWAP,2)
	s_waitcnt lgkmcnt(0)
	v_pk_add_f32 v[60:61], v[60:61], v[62:63]
	ds_swizzle_b32 v63, v61 offset:swizzle(SWAP,1)
	ds_swizzle_b32 v62, v60 offset:swizzle(SWAP,1)
	s_waitcnt lgkmcnt(0)
	v_pk_add_f32 v[60:61], v[60:61], v[62:63]
	ds_bpermute_b32 v63, v0, v61
	ds_bpermute_b32 v62, v23, v60
	s_waitcnt lgkmcnt(0)
	v_pk_add_f32 v[60:61], v[60:61], v[62:63]
	s_nop 0
	v_pk_fma_f32 v[60:61], v[60:61], s[58:59], v[154:155] op_sel_hi:[1,0,0]
	s_nop 0
	v_mul_f32_e32 v0, 0x4b800000, v61
	v_cmp_gt_f32_e64 s[2:3], s46, v61
	v_mul_f32_e32 v23, 0x4b800000, v60
	v_cmp_gt_f32_e32 vcc, s46, v60
	v_cndmask_b32_e64 v0, v61, v0, s[2:3]
	v_rsq_f32_e32 v0, v0
	v_cndmask_b32_e32 v23, v60, v23, vcc
	v_rsq_f32_e32 v23, v23
	v_mul_f32_e32 v60, 0x45800000, v0
	v_cndmask_b32_e64 v0, v0, v60, s[2:3]
	v_mul_f32_e32 v61, 0x45800000, v23
	v_cndmask_b32_e32 v60, v23, v61, vcc
	v_pk_mul_f32 v[26:27], v[26:27], v[0:1] op_sel_hi:[1,0]
	v_pk_mul_f32 v[28:29], v[28:29], v[0:1] op_sel_hi:[1,0]
	v_pk_mul_f32 v[30:31], v[30:31], v[0:1] op_sel_hi:[1,0]
	v_pk_mul_f32 v[32:33], v[32:33], v[0:1] op_sel_hi:[1,0]
	v_pk_mul_f32 v[42:43], v[42:43], v[60:61] op_sel_hi:[1,0]
	v_pk_mul_f32 v[44:45], v[44:45], v[60:61] op_sel_hi:[1,0]
	v_pk_mul_f32 v[46:47], v[46:47], v[60:61] op_sel_hi:[1,0]
	v_pk_mul_f32 v[48:49], v[48:49], v[60:61] op_sel_hi:[1,0]
	v_pk_mul_f32 v[34:35], v[34:35], v[0:1] op_sel_hi:[1,0]
	v_pk_mul_f32 v[36:37], v[36:37], v[0:1] op_sel_hi:[1,0]
	v_pk_mul_f32 v[38:39], v[38:39], v[0:1] op_sel_hi:[1,0]
	v_pk_mul_f32 v[40:41], v[40:41], v[0:1] op_sel_hi:[1,0]
	v_pk_mul_f32 v[50:51], v[50:51], v[60:61] op_sel_hi:[1,0]
	v_pk_mul_f32 v[52:53], v[52:53], v[60:61] op_sel_hi:[1,0]
	v_pk_mul_f32 v[54:55], v[54:55], v[60:61] op_sel_hi:[1,0]
	v_pk_mul_f32 v[56:57], v[56:57], v[60:61] op_sel_hi:[1,0]
	v_pk_mul_f32 v[28:29], v[8:9], v[28:29]
	v_pk_mul_f32 v[26:27], v[6:7], v[26:27]
	v_pk_mul_f32 v[32:33], v[4:5], v[32:33]
	v_pk_mul_f32 v[30:31], v[2:3], v[30:31]
	v_pk_mul_f32 v[44:45], v[8:9], v[44:45]
	v_pk_mul_f32 v[42:43], v[6:7], v[42:43]
	v_pk_mul_f32 v[48:49], v[4:5], v[48:49]
	v_pk_mul_f32 v[46:47], v[2:3], v[46:47]
	v_pk_mul_f32 v[36:37], v[16:17], v[36:37]
	v_pk_mul_f32 v[34:35], v[14:15], v[34:35]
	v_pk_mul_f32 v[40:41], v[12:13], v[40:41]
	v_pk_mul_f32 v[38:39], v[10:11], v[38:39]
	v_pk_mul_f32 v[52:53], v[16:17], v[52:53]
	v_pk_mul_f32 v[50:51], v[14:15], v[50:51]
	v_pk_mul_f32 v[56:57], v[12:13], v[56:57]
	v_pk_mul_f32 v[54:55], v[10:11], v[54:55]
	v_cvt_pk_bf16_f32 v26, v26, v27
	v_cvt_pk_bf16_f32 v27, v28, v29
	v_cvt_pk_bf16_f32 v28, v30, v31
	v_cvt_pk_bf16_f32 v29, v32, v33
	v_cvt_pk_bf16_f32 v30, v42, v43
	v_cvt_pk_bf16_f32 v31, v44, v45
	v_cvt_pk_bf16_f32 v32, v46, v47
	v_cvt_pk_bf16_f32 v33, v48, v49
	v_cvt_pk_bf16_f32 v34, v34, v35
	v_cvt_pk_bf16_f32 v35, v36, v37
	v_cvt_pk_bf16_f32 v36, v38, v39
	v_cvt_pk_bf16_f32 v37, v40, v41
	v_cvt_pk_bf16_f32 v38, v50, v51
	v_cvt_pk_bf16_f32 v39, v52, v53
	v_cvt_pk_bf16_f32 v40, v54, v55
	v_cvt_pk_bf16_f32 v41, v56, v57
	global_store_dwordx4 v[24:25], v[26:29], off sc1
	global_store_dwordx4 v[58:59], v[30:33], off sc1
	global_store_dwordx4 v[24:25], v[34:37], off offset:1024 sc1
	global_store_dwordx4 v[58:59], v[38:41], off offset:1024 sc1
	s_branch .Ln1_done
; __device__ __forceinline__ void store8bf(bf16_t* p, f32x4 v0, f32x4 v1) { u32x4 w; w.x = cvt_pk_bf16(v0[0], v0[1]); w.y = cvt_pk_bf16(v0[2], v0[3]); w.z = cvt_pk_bf16(v1[0], v1[1]); w.w = cvt_pk_bf16(v1[2], v1[3]); *(u32x4*)p = w; }
; template <int M> __device__ __forceinline__ float shx(float v) { return __builtin_bit_cast(float, __builtin_amdgcn_ds_swizzle(__builtin_bit_cast(int, v), (M << 10) | 0x1f)); }
; __device__ __forceinline__ float xhalf(float v) {
;   int l = (int)__builtin_amdgcn_mbcnt_hi(~0u, __builtin_amdgcn_mbcnt_lo(~0u, 0u)); asm volatile("" : "+v"(l));
;   return __builtin_bit_cast(float, __builtin_amdgcn_ds_bpermute((l ^ 32) << 2, __builtin_bit_cast(int, v))); }
; __device__ __forceinline__ float sum32(float v) { return v + xhalf(v); }
; __device__ __forceinline__ float max32(float v) { return __builtin_fmaxf(v, xhalf(v)); }
; __device__ __forceinline__ float wave_sum(float v) {
;   v += shx<16>(v); v += shx<8>(v); v += shx<4>(v); v += shx<2>(v); v += shx<1>(v); return sum32(v);
; }
; __device__ __forceinline__ void norm_phase(const float* H, const float* g, bf16_t* HN) {
;     ...
;   for (int row = gw; row < NREAL + 64; row += 2 * nw) {
;     const int row2 = row + nw < NREAL + 64 ? row + nw : row;
;     const float* p = H + (size_t)row * DM + lane * 8; const float* p2 = H + (size_t)row2 * DM + lane * 8; f32x4 v[4], u[4]; float ss = 0.f, ss2 = 0.f;
; #pragma unroll
;     for (int i = 0; i < 4; ++i) { v[i] = *(const f32x4*)(p + 512 * (i >> 1) + 4 * (i & 1)); u[i] = *(const f32x4*)(p2 + 512 * (i >> 1) + 4 * (i & 1)); }
; #pragma unroll
;     for (int i = 0; i < 4; ++i) { ss += v[i][0] * v[i][0] + v[i][1] * v[i][1] + v[i][2] * v[i][2] + v[i][3] * v[i][3]; ss2 += u[i][0] * u[i][0] + u[i][1] * u[i][1] + u[i][2] * u[i][2] + u[i][3] * u[i][3]; }
;     ss = wave_sum(ss); ss2 = wave_sum(ss2); const float rs = rsqrtf(ss * (1.0f / 1024.0f) + 1e-6f), rs2 = rsqrtf(ss2 * (1.0f / 1024.0f) + 1e-6f);
;     bf16_t* q = HN + (size_t)row * DM + lane * 8; bf16_t* q2 = HN + (size_t)row2 * DM + lane * 8;
; #pragma unroll
;     for (int i = 0; i < 2; ++i) { store8bf(q + 512 * i, v[2 * i] * rs * gv[2 * i], v[2 * i + 1] * rs * gv[2 * i + 1]); store8bf(q2 + 512 * i, u[2 * i] * rs2 * gv[2 * i], u[2 * i + 1] * rs2 * gv[2 * i + 1]); }
;   }
.Ln1_lastB:
	s_waitcnt vmcnt(0)
	v_lshlrev_b32_e32 v0, 2, v210
	v_xor_b32_e32 v0, 0x80, v0
	v_mov_b32_e32 v23, v0
	v_mov_b32_e32 v62, v73
	v_mov_b32_e32 v63, v77
	v_mov_b32_e32 v70, v81
	v_mov_b32_e32 v71, v89
	v_mov_b32_e32 v60, v72
	v_mov_b32_e32 v61, v76
	v_mov_b32_e32 v68, v80
	v_mov_b32_e32 v69, v88
	v_pk_mul_f32 v[62:63], v[62:63], v[62:63]
	v_pk_mul_f32 v[70:71], v[70:71], v[70:71]
	v_pk_fma_f32 v[60:61], v[60:61], v[60:61], v[62:63]
	v_mov_b32_e32 v62, v82
	v_mov_b32_e32 v63, v90
	v_pk_fma_f32 v[68:69], v[68:69], v[68:69], v[70:71]
	v_mov_b32_e32 v64, v74
	v_mov_b32_e32 v65, v78
	v_mov_b32_e32 v70, v83
	v_mov_b32_e32 v71, v91
	v_pk_fma_f32 v[62:63], v[62:63], v[62:63], v[68:69]
	v_mov_b32_e32 v68, v93
	v_mov_b32_e32 v69, v97
	v_mov_b32_e32 v66, v75
	v_mov_b32_e32 v67, v79
	v_pk_fma_f32 v[60:61], v[64:65], v[64:65], v[60:61]
	v_mov_b32_e32 v64, v92
	v_mov_b32_e32 v65, v96
	v_pk_mul_f32 v[68:69], v[68:69], v[68:69]
	v_pk_fma_f32 v[62:63], v[70:71], v[70:71], v[62:63]
	v_mov_b32_e32 v70, v101
	v_mov_b32_e32 v71, v129
	v_pk_fma_f32 v[60:61], v[66:67], v[66:67], v[60:61]
	v_mov_b32_e32 v66, v94
	v_mov_b32_e32 v67, v98
	v_pk_fma_f32 v[64:65], v[64:65], v[64:65], v[68:69]
	v_mov_b32_e32 v68, v100
	v_mov_b32_e32 v69, v128
	v_pk_mul_f32 v[70:71], v[70:71], v[70:71]
	v_pk_fma_f32 v[64:65], v[66:67], v[66:67], v[64:65]
	v_pk_fma_f32 v[68:69], v[68:69], v[68:69], v[70:71]
	v_mov_b32_e32 v70, v95
	v_mov_b32_e32 v71, v99
	v_mov_b32_e32 v66, v102
	v_mov_b32_e32 v67, v130
	v_pk_fma_f32 v[66:67], v[66:67], v[66:67], v[68:69]
	v_mov_b32_e32 v68, v103
	v_mov_b32_e32 v69, v131
	v_pk_fma_f32 v[64:65], v[70:71], v[70:71], v[64:65]
	v_mov_b32_e32 v71, v60
	v_pk_fma_f32 v[66:67], v[68:69], v[68:69], v[66:67]
	v_mov_b32_e32 v70, v64
	v_mov_b32_e32 v60, v65
	v_mov_b32_e32 v69, v62
	v_mov_b32_e32 v68, v66
	v_pk_add_f32 v[60:61], v[70:71], v[60:61]
	v_mov_b32_e32 v62, v67
	v_pk_add_f32 v[60:61], v[60:61], v[68:69]
	s_nop 0
	v_pk_add_f32 v[60:61], v[60:61], v[62:63]
	ds_swizzle_b32 v63, v61 offset:swizzle(SWAP,16)
	ds_swizzle_b32 v62, v60 offset:swizzle(SWAP,16)
	s_waitcnt lgkmcnt(0)
	v_pk_add_f32 v[60:61], v[60:61], v[62:63]
	ds_swizzle_b32 v63, v61 offset:swizzle(SWAP,8)
	ds_swizzle_b32 v62, v60 offset:swizzle(SWAP,8)
	s_waitcnt lgkmcnt(0)
	v_pk_add_f32 v[60:61], v[60:61], v[62:63]
	ds_swizzle_b32 v63, v61 offset:swizzle(SWAP,4)
	ds_swizzle_b32 v62, v60 offset:swizzle(SWAP,4)
	s_waitcnt lgkmcnt(0)
	v_pk_add_f32 v[60:61], v[60:61], v[62:63]
	ds_swizzle_b32 v63, v61 offset:swizzle(SWAP,2)
	ds_swizzle_b32 v62, v60 offset:swizzle(SWAP,2)
	s_waitcnt lgkmcnt(0)
	v_pk_add_f32 v[60:61], v[60:61], v[62:63]
	ds_swizzle_b32 v63, v61 offset:swizzle(SWAP,1)
	ds_swizzle_b32 v62, v60 offset:swizzle(SWAP,1)
	s_waitcnt lgkmcnt(0)
	v_pk_add_f32 v[60:61], v[60:61], v[62:63]
	ds_bpermute_b32 v63, v0, v61
	ds_bpermute_b32 v62, v23, v60
	s_waitcnt lgkmcnt(0)
	v_pk_add_f32 v[60:61], v[60:61], v[62:63]
	s_nop 0
	v_pk_fma_f32 v[60:61], v[60:61], s[58:59], v[154:155] op_sel_hi:[1,0,0]
	s_nop 0
	v_mul_f32_e32 v0, 0x4b800000, v61
	v_cmp_gt_f32_e64 s[2:3], s46, v61
	v_mul_f32_e32 v23, 0x4b800000, v60
	v_cmp_gt_f32_e32 vcc, s46, v60
	v_cndmask_b32_e64 v0, v61, v0, s[2:3]
	v_rsq_f32_e32 v0, v0
	v_cndmask_b32_e32 v23, v60, v23, vcc
	v_rsq_f32_e32 v23, v23
	v_mul_f32_e32 v60, 0x45800000, v0
	v_cndmask_b32_e64 v0, v0, v60, s[2:3]
	v_mul_f32_e32 v61, 0x45800000, v23
	v_cndmask_b32_e32 v60, v23, v61, vcc
	v_pk_mul_f32 v[72:73], v[72:73], v[0:1] op_sel_hi:[1,0]
	v_pk_mul_f32 v[74:75], v[74:75], v[0:1] op_sel_hi:[1,0]
	v_pk_mul_f32 v[76:77], v[76:77], v[0:1] op_sel_hi:[1,0]
	v_pk_mul_f32 v[78:79], v[78:79], v[0:1] op_sel_hi:[1,0]
	v_pk_mul_f32 v[92:93], v[92:93], v[60:61] op_sel_hi:[1,0]
	v_pk_mul_f32 v[94:95], v[94:95], v[60:61] op_sel_hi:[1,0]
	v_pk_mul_f32 v[96:97], v[96:97], v[60:61] op_sel_hi:[1,0]
	v_pk_mul_f32 v[98:99], v[98:99], v[60:61] op_sel_hi:[1,0]
	v_pk_mul_f32 v[80:81], v[80:81], v[0:1] op_sel_hi:[1,0]
	v_pk_mul_f32 v[82:83], v[82:83], v[0:1] op_sel_hi:[1,0]
	v_pk_mul_f32 v[88:89], v[88:89], v[0:1] op_sel_hi:[1,0]
	v_pk_mul_f32 v[90:91], v[90:91], v[0:1] op_sel_hi:[1,0]
	v_pk_mul_f32 v[100:101], v[100:101], v[60:61] op_sel_hi:[1,0]
	v_pk_mul_f32 v[102:103], v[102:103], v[60:61] op_sel_hi:[1,0]
	v_pk_mul_f32 v[128:129], v[128:129], v[60:61] op_sel_hi:[1,0]
	v_pk_mul_f32 v[130:131], v[130:131], v[60:61] op_sel_hi:[1,0]
	v_pk_mul_f32 v[74:75], v[8:9], v[74:75]
	v_pk_mul_f32 v[72:73], v[6:7], v[72:73]
	v_pk_mul_f32 v[78:79], v[4:5], v[78:79]
	v_pk_mul_f32 v[76:77], v[2:3], v[76:77]
	v_pk_mul_f32 v[94:95], v[8:9], v[94:95]
	v_pk_mul_f32 v[92:93], v[6:7], v[92:93]
	v_pk_mul_f32 v[98:99], v[4:5], v[98:99]
	v_pk_mul_f32 v[96:97], v[2:3], v[96:97]
	v_pk_mul_f32 v[82:83], v[16:17], v[82:83]
	v_pk_mul_f32 v[80:81], v[14:15], v[80:81]
	v_pk_mul_f32 v[90:91], v[12:13], v[90:91]
	v_pk_mul_f32 v[88:89], v[10:11], v[88:89]
	v_pk_mul_f32 v[102:103], v[16:17], v[102:103]
	v_pk_mul_f32 v[100:101], v[14:15], v[100:101]
	v_pk_mul_f32 v[130:131], v[12:13], v[130:131]
	v_pk_mul_f32 v[128:129], v[10:11], v[128:129]
	v_cvt_pk_bf16_f32 v72, v72, v73
	v_cvt_pk_bf16_f32 v73, v74, v75
	v_cvt_pk_bf16_f32 v74, v76, v77
	v_cvt_pk_bf16_f32 v75, v78, v79
	v_cvt_pk_bf16_f32 v76, v92, v93
	v_cvt_pk_bf16_f32 v77, v94, v95
	v_cvt_pk_bf16_f32 v78, v96, v97
	v_cvt_pk_bf16_f32 v79, v98, v99
	v_cvt_pk_bf16_f32 v80, v80, v81
	v_cvt_pk_bf16_f32 v81, v82, v83
	v_cvt_pk_bf16_f32 v82, v88, v89
	v_cvt_pk_bf16_f32 v83, v90, v91
	v_cvt_pk_bf16_f32 v88, v100, v101
	v_cvt_pk_bf16_f32 v89, v102, v103
	v_cvt_pk_bf16_f32 v90, v128, v129
	v_cvt_pk_bf16_f32 v91, v130, v131
	global_store_dwordx4 v[132:133], v[72:75], off sc1
	global_store_dwordx4 v[134:135], v[76:79], off sc1
	global_store_dwordx4 v[132:133], v[80:83], off offset:1024 sc1
	global_store_dwordx4 v[134:135], v[88:91], off offset:1024 sc1
	s_branch .Ln1_done
; __device__ __forceinline__ void store8bf(bf16_t* p, f32x4 v0, f32x4 v1) { u32x4 w; w.x = cvt_pk_bf16(v0[0], v0[1]); w.y = cvt_pk_bf16(v0[2], v0[3]); w.z = cvt_pk_bf16(v1[0], v1[1]); w.w = cvt_pk_bf16(v1[2], v1[3]); *(u32x4*)p = w; }
; template <int M> __device__ __forceinline__ float shx(float v) { return __builtin_bit_cast(float, __builtin_amdgcn_ds_swizzle(__builtin_bit_cast(int, v), (M << 10) | 0x1f)); }
; __device__ __forceinline__ float xhalf(float v) {
;   int l = (int)__builtin_amdgcn_mbcnt_hi(~0u, __builtin_amdgcn_mbcnt_lo(~0u, 0u)); asm volatile("" : "+v"(l));
;   return __builtin_bit_cast(float, __builtin_amdgcn_ds_bpermute((l ^ 32) << 2, __builtin_bit_cast(int, v))); }
; __device__ __forceinline__ float sum32(float v) { return v + xhalf(v); }
; __device__ __forceinline__ float max32(float v) { return __builtin_fmaxf(v, xhalf(v)); }
; __device__ __forceinline__ float wave_sum(float v) {
;   v += shx<16>(v); v += shx<8>(v); v += shx<4>(v); v += shx<2>(v); v += shx<1>(v); return sum32(v);
; }
; __device__ __forceinline__ void norm_phase(const float* H, const float* g, bf16_t* HN) {
;     ...
;   for (int row = gw; row < NREAL + 64; row += 2 * nw) {
;     const int row2 = row + nw < NREAL + 64 ? row + nw : row;
;     const float* p = H + (size_t)row * DM + lane * 8; const float* p2 = H + (size_t)row2 * DM + lane * 8; f32x4 v[4], u[4]; float ss = 0.f, ss2 = 0.f;
; #pragma unroll
;     for (int i = 0; i < 4; ++i) { v[i] = *(const f32x4*)(p + 512 * (i >> 1) + 4 * (i & 1)); u[i] = *(const f32x4*)(p2 + 512 * (i >> 1) + 4 * (i & 1)); }
; #pragma unroll
;     for (int i = 0; i < 4; ++i) { ss += v[i][0] * v[i][0] + v[i][1] * v[i][1] + v[i][2] * v[i][2] + v[i][3] * v[i][3]; ss2 += u[i][0] * u[i][0] + u[i][1] * u[i][1] + u[i][2] * u[i][2] + u[i][3] * u[i][3]; }
;     ss = wave_sum(ss); ss2 = wave_sum(ss2); const float rs = rsqrtf(ss * (1.0f / 1024.0f) + 1e-6f), rs2 = rsqrtf(ss2 * (1.0f / 1024.0f) + 1e-6f);
;     bf16_t* q = HN + (size_t)row * DM + lane * 8; bf16_t* q2 = HN + (size_t)row2 * DM + lane * 8;
; #pragma unroll
;     for (int i = 0; i < 2; ++i) { store8bf(q + 512 * i, v[2 * i] * rs * gv[2 * i], v[2 * i + 1] * rs * gv[2 * i + 1]); store8bf(q2 + 512 * i, u[2 * i] * rs2 * gv[2 * i], u[2 * i + 1] * rs2 * gv[2 * i + 1]); }
;   }
.Ln1_lastA:
	s_waitcnt vmcnt(0)
	v_lshlrev_b32_e32 v0, 2, v210
	v_xor_b32_e32 v0, 0x80, v0
	v_mov_b32_e32 v23, v0
	v_mov_b32_e32 v62, v27
	v_mov_b32_e32 v63, v31
	v_mov_b32_e32 v70, v35
	v_mov_b32_e32 v71, v39
	v_mov_b32_e32 v60, v26
	v_mov_b32_e32 v61, v30
	v_mov_b32_e32 v68, v34
	v_mov_b32_e32 v69, v38
	v_pk_mul_f32 v[62:63], v[62:63], v[62:63]
	v_pk_mul_f32 v[70:71], v[70:71], v[70:71]
	v_pk_fma_f32 v[60:61], v[60:61], v[60:61], v[62:63]
	v_mov_b32_e32 v62, v36
	v_mov_b32_e32 v63, v40
	v_pk_fma_f32 v[68:69], v[68:69], v[68:69], v[70:71]
	v_mov_b32_e32 v64, v28
	v_mov_b32_e32 v65, v32
	v_mov_b32_e32 v70, v37
	v_mov_b32_e32 v71, v41
	v_pk_fma_f32 v[62:63], v[62:63], v[62:63], v[68:69]
	v_mov_b32_e32 v68, v43
	v_mov_b32_e32 v69, v47
	v_mov_b32_e32 v66, v29
	v_mov_b32_e32 v67, v33
	v_pk_fma_f32 v[60:61], v[64:65], v[64:65], v[60:61]
	v_mov_b32_e32 v64, v42
	v_mov_b32_e32 v65, v46
	v_pk_mul_f32 v[68:69], v[68:69], v[68:69]
	v_pk_fma_f32 v[62:63], v[70:71], v[70:71], v[62:63]
	v_mov_b32_e32 v70, v51
	v_mov_b32_e32 v71, v55
	v_pk_fma_f32 v[60:61], v[66:67], v[66:67], v[60:61]
	v_mov_b32_e32 v66, v44
	v_mov_b32_e32 v67, v48
	v_pk_fma_f32 v[64:65], v[64:65], v[64:65], v[68:69]
	v_mov_b32_e32 v68, v50
	v_mov_b32_e32 v69, v54
	v_pk_mul_f32 v[70:71], v[70:71], v[70:71]
	v_pk_fma_f32 v[64:65], v[66:67], v[66:67], v[64:65]
	v_pk_fma_f32 v[68:69], v[68:69], v[68:69], v[70:71]
	v_mov_b32_e32 v70, v45
	v_mov_b32_e32 v71, v49
	v_mov_b32_e32 v66, v52
	v_mov_b32_e32 v67, v56
	v_pk_fma_f32 v[66:67], v[66:67], v[66:67], v[68:69]
	v_mov_b32_e32 v68, v53
	v_mov_b32_e32 v69, v57
	v_pk_fma_f32 v[64:65], v[70:71], v[70:71], v[64:65]
	v_mov_b32_e32 v71, v60
	v_pk_fma_f32 v[66:67], v[68:69], v[68:69], v[66:67]
	v_mov_b32_e32 v70, v64
	v_mov_b32_e32 v60, v65
	v_mov_b32_e32 v69, v62
	v_mov_b32_e32 v68, v66
	v_pk_add_f32 v[60:61], v[70:71], v[60:61]
	v_mov_b32_e32 v62, v67
	v_pk_add_f32 v[60:61], v[60:61], v[68:69]
	s_nop 0
	v_pk_add_f32 v[60:61], v[60:61], v[62:63]
	ds_swizzle_b32 v63, v61 offset:swizzle(SWAP,16)
	ds_swizzle_b32 v62, v60 offset:swizzle(SWAP,16)
	s_waitcnt lgkmcnt(0)
	v_pk_add_f32 v[60:61], v[60:61], v[62:63]
	ds_swizzle_b32 v63, v61 offset:swizzle(SWAP,8)
	ds_swizzle_b32 v62, v60 offset:swizzle(SWAP,8)
	s_waitcnt lgkmcnt(0)
	v_pk_add_f32 v[60:61], v[60:61], v[62:63]
	ds_swizzle_b32 v63, v61 offset:swizzle(SWAP,4)
	ds_swizzle_b32 v62, v60 offset:swizzle(SWAP,4)
	s_waitcnt lgkmcnt(0)
	v_pk_add_f32 v[60:61], v[60:61], v[62:63]
	ds_swizzle_b32 v63, v61 offset:swizzle(SWAP,2)
	ds_swizzle_b32 v62, v60 offset:swizzle(SWAP,2)
	s_waitcnt lgkmcnt(0)
	v_pk_add_f32 v[60:61], v[60:61], v[62:63]
	ds_swizzle_b32 v63, v61 offset:swizzle(SWAP,1)
	ds_swizzle_b32 v62, v60 offset:swizzle(SWAP,1)
	s_waitcnt lgkmcnt(0)
	v_pk_add_f32 v[60:61], v[60:61], v[62:63]
	ds_bpermute_b32 v63, v0, v61
	ds_bpermute_b32 v62, v23, v60
	s_waitcnt lgkmcnt(0)
	v_pk_add_f32 v[60:61], v[60:61], v[62:63]
	s_nop 0
	v_pk_fma_f32 v[60:61], v[60:61], s[58:59], v[154:155] op_sel_hi:[1,0,0]
	s_nop 0
	v_mul_f32_e32 v0, 0x4b800000, v61
	v_cmp_gt_f32_e64 s[2:3], s46, v61
	v_mul_f32_e32 v23, 0x4b800000, v60
	v_cmp_gt_f32_e32 vcc, s46, v60
	v_cndmask_b32_e64 v0, v61, v0, s[2:3]
	v_rsq_f32_e32 v0, v0
	v_cndmask_b32_e32 v23, v60, v23, vcc
	v_rsq_f32_e32 v23, v23
	v_mul_f32_e32 v60, 0x45800000, v0
	v_cndmask_b32_e64 v0, v0, v60, s[2:3]
	v_mul_f32_e32 v61, 0x45800000, v23
	v_cndmask_b32_e32 v60, v23, v61, vcc
	v_pk_mul_f32 v[26:27], v[26:27], v[0:1] op_sel_hi:[1,0]
	v_pk_mul_f32 v[28:29], v[28:29], v[0:1] op_sel_hi:[1,0]
	v_pk_mul_f32 v[30:31], v[30:31], v[0:1] op_sel_hi:[1,0]
	v_pk_mul_f32 v[32:33], v[32:33], v[0:1] op_sel_hi:[1,0]
	v_pk_mul_f32 v[42:43], v[42:43], v[60:61] op_sel_hi:[1,0]
	v_pk_mul_f32 v[44:45], v[44:45], v[60:61] op_sel_hi:[1,0]
	v_pk_mul_f32 v[46:47], v[46:47], v[60:61] op_sel_hi:[1,0]
	v_pk_mul_f32 v[48:49], v[48:49], v[60:61] op_sel_hi:[1,0]
	v_pk_mul_f32 v[34:35], v[34:35], v[0:1] op_sel_hi:[1,0]
	v_pk_mul_f32 v[36:37], v[36:37], v[0:1] op_sel_hi:[1,0]
	v_pk_mul_f32 v[38:39], v[38:39], v[0:1] op_sel_hi:[1,0]
	v_pk_mul_f32 v[40:41], v[40:41], v[0:1] op_sel_hi:[1,0]
	v_pk_mul_f32 v[50:51], v[50:51], v[60:61] op_sel_hi:[1,0]
	v_pk_mul_f32 v[52:53], v[52:53], v[60:61] op_sel_hi:[1,0]
	v_pk_mul_f32 v[54:55], v[54:55], v[60:61] op_sel_hi:[1,0]
	v_pk_mul_f32 v[56:57], v[56:57], v[60:61] op_sel_hi:[1,0]
	v_pk_mul_f32 v[28:29], v[8:9], v[28:29]
	v_pk_mul_f32 v[26:27], v[6:7], v[26:27]
	v_pk_mul_f32 v[32:33], v[4:5], v[32:33]
	v_pk_mul_f32 v[30:31], v[2:3], v[30:31]
	v_pk_mul_f32 v[44:45], v[8:9], v[44:45]
	v_pk_mul_f32 v[42:43], v[6:7], v[42:43]
	v_pk_mul_f32 v[48:49], v[4:5], v[48:49]
	v_pk_mul_f32 v[46:47], v[2:3], v[46:47]
	v_pk_mul_f32 v[36:37], v[16:17], v[36:37]
	v_pk_mul_f32 v[34:35], v[14:15], v[34:35]
	v_pk_mul_f32 v[40:41], v[12:13], v[40:41]
	v_pk_mul_f32 v[38:39], v[10:11], v[38:39]
	v_pk_mul_f32 v[52:53], v[16:17], v[52:53]
	v_pk_mul_f32 v[50:51], v[14:15], v[50:51]
	v_pk_mul_f32 v[56:57], v[12:13], v[56:57]
	v_pk_mul_f32 v[54:55], v[10:11], v[54:55]
	v_cvt_pk_bf16_f32 v26, v26, v27
	v_cvt_pk_bf16_f32 v27, v28, v29
	v_cvt_pk_bf16_f32 v28, v30, v31
	v_cvt_pk_bf16_f32 v29, v32, v33
	v_cvt_pk_bf16_f32 v30, v42, v43
	v_cvt_pk_bf16_f32 v31, v44, v45
	v_cvt_pk_bf16_f32 v32, v46, v47
	v_cvt_pk_bf16_f32 v33, v48, v49
	v_cvt_pk_bf16_f32 v34, v34, v35
	v_cvt_pk_bf16_f32 v35, v36, v37
	v_cvt_pk_bf16_f32 v36, v38, v39
	v_cvt_pk_bf16_f32 v37, v40, v41
	v_cvt_pk_bf16_f32 v38, v50, v51
	v_cvt_pk_bf16_f32 v39, v52, v53
	v_cvt_pk_bf16_f32 v40, v54, v55
	v_cvt_pk_bf16_f32 v41, v56, v57
	global_store_dwordx4 v[24:25], v[26:29], off sc1
	global_store_dwordx4 v[58:59], v[30:33], off sc1
	global_store_dwordx4 v[24:25], v[34:37], off offset:1024 sc1
	global_store_dwordx4 v[58:59], v[38:41], off offset:1024 sc1

; __device__ __forceinline__ void store8bf(bf16_t* p, f32x4 v0, f32x4 v1) { u32x4 w; w.x = cvt_pk_bf16(v0[0], v0[1]); w.y = cvt_pk_bf16(v0[2], v0[3]); w.z = cvt_pk_bf16(v1[0], v1[1]); w.w = cvt_pk_bf16(v1[2], v1[3]); *(u32x4*)p = w; }
; template <int M> __device__ __forceinline__ float shx(float v) { return __builtin_bit_cast(float, __builtin_amdgcn_ds_swizzle(__builtin_bit_cast(int, v), (M << 10) | 0x1f)); }
; __device__ __forceinline__ float xhalf(float v) {
;   int l = (int)__builtin_amdgcn_mbcnt_hi(~0u, __builtin_amdgcn_mbcnt_lo(~0u, 0u)); asm volatile("" : "+v"(l));
;   return __builtin_bit_cast(float, __builtin_amdgcn_ds_bpermute((l ^ 32) << 2, __builtin_bit_cast(int, v))); }
; __device__ __forceinline__ float sum32(float v) { return v + xhalf(v); }
; __device__ __forceinline__ float max32(float v) { return __builtin_fmaxf(v, xhalf(v)); }
; __device__ __forceinline__ float wave_sum(float v) {
;   v += shx<16>(v); v += shx<8>(v); v += shx<4>(v); v += shx<2>(v); v += shx<1>(v); return sum32(v);
; }
; __device__ __forceinline__ void norm_phase(const float* H, const float* g, bf16_t* HN) {
;     ...
;   for (int row = gw; row < NREAL + 64; row += 2 * nw) {
;     const int row2 = row + nw < NREAL + 64 ? row + nw : row;
;     const float* p = H + (size_t)row * DM + lane * 8; const float* p2 = H + (size_t)row2 * DM + lane * 8; f32x4 v[4], u[4]; float ss = 0.f, ss2 = 0.f;
; #pragma unroll
;     for (int i = 0; i < 4; ++i) { v[i] = *(const f32x4*)(p + 512 * (i >> 1) + 4 * (i & 1)); u[i] = *(const f32x4*)(p2 + 512 * (i >> 1) + 4 * (i & 1)); }
; #pragma unroll
;     for (int i = 0; i < 4; ++i) { ss += v[i][0] * v[i][0] + v[i][1] * v[i][1] + v[i][2] * v[i][2] + v[i][3] * v[i][3]; ss2 += u[i][0] * u[i][0] + u[i][1] * u[i][1] + u[i][2] * u[i][2] + u[i][3] * u[i][3]; }
;     ss = wave_sum(ss); ss2 = wave_sum(ss2); const float rs = rsqrtf(ss * (1.0f / 1024.0f) + 1e-6f), rs2 = rsqrtf(ss2 * (1.0f / 1024.0f) + 1e-6f);
;     bf16_t* q = HN + (size_t)row * DM + lane * 8; bf16_t* q2 = HN + (size_t)row2 * DM + lane * 8;
; #pragma unroll
;     for (int i = 0; i < 2; ++i) { store8bf(q + 512 * i, v[2 * i] * rs * gv[2 * i], v[2 * i + 1] * rs * gv[2 * i + 1]); store8bf(q2 + 512 * i, u[2 * i] * rs2 * gv[2 * i], u[2 * i + 1] * rs2 * gv[2 * i + 1]); }
;   }
.LBB0_1501:
	v_readfirstlane_b32 s0, v54
	s_nop 3
	s_add_i32 s9, s0, s24
	s_cmp_lt_i32 s9, s49
	s_cselect_b32 s9, s9, s0
	s_lshl_b32 s10, s0, 12
	s_lshl_b32 s4, s9, 12
	v_mov_b32_e32 v62, s10
	v_mov_b32_e32 v63, 0
	v_lshl_add_u64 v[58:59], v[50:51], 0, v[62:63]
	v_mov_b32_e32 v62, s4
	v_lshl_add_u64 v[60:61], v[50:51], 0, v[62:63]
	global_load_dwordx4 v[46:49], v[58:59], off
	global_load_dwordx4 v[42:45], v[58:59], off offset:16
	global_load_dwordx4 v[38:41], v[60:61], off
	global_load_dwordx4 v[34:37], v[60:61], off offset:16
	global_load_dwordx4 v[30:33], v[58:59], off offset:2048
	global_load_dwordx4 v[26:29], v[58:59], off offset:2064
	global_load_dwordx4 v[22:25], v[60:61], off offset:2048
	global_load_dwordx4 v[18:21], v[60:61], off offset:2064
	s_lshl_b32 s10, s0, 11
	s_lshl_b32 s4, s9, 11
	v_mov_b32_e32 v62, s10
	v_lshl_add_u64 v[54:55], v[52:53], 0, v[62:63]
	v_mov_b32_e32 v62, s4
	v_lshl_add_u64 v[56:57], v[52:53], 0, v[62:63]
	s_lshl_b32 s8, s24, 1
	s_add_i32 s1, s0, s8
	s_cmp_lt_i32 s1, s49
	s_cbranch_scc0 .Ln2_lastA_first
	s_add_i32 s9, s1, s24
	s_cmp_lt_i32 s9, s49
	s_cselect_b32 s9, s9, s1
	s_lshl_b32 s10, s1, 12
	s_lshl_b32 s4, s9, 12
	v_mov_b32_e32 v62, s10
	v_mov_b32_e32 v63, 0
	v_lshl_add_u64 v[58:59], v[50:51], 0, v[62:63]
	v_mov_b32_e32 v62, s4
	v_lshl_add_u64 v[60:61], v[50:51], 0, v[62:63]
	global_load_dwordx4 v[100:103], v[58:59], off
	global_load_dwordx4 v[96:99], v[58:59], off offset:16
	global_load_dwordx4 v[92:95], v[60:61], off
	global_load_dwordx4 v[88:91], v[60:61], off offset:16
	global_load_dwordx4 v[82:85], v[58:59], off offset:2048
	global_load_dwordx4 v[78:81], v[58:59], off offset:2064
	global_load_dwordx4 v[74:77], v[60:61], off offset:2048
	global_load_dwordx4 v[70:73], v[60:61], off offset:2064
	s_lshl_b32 s10, s1, 11
	s_lshl_b32 s4, s9, 11
	v_mov_b32_e32 v62, s10
	v_lshl_add_u64 v[128:129], v[52:53], 0, v[62:63]
	v_mov_b32_e32 v62, s4
	v_lshl_add_u64 v[130:131], v[52:53], 0, v[62:63]
	s_waitcnt vmcnt(8)
	v_mov_b32_e32 v60, v47
	v_mov_b32_e32 v61, v43
	v_mov_b32_e32 v58, v46
	v_mov_b32_e32 v59, v42
	v_pk_mul_f32 v[60:61], v[60:61], v[60:61]
	v_mov_b32_e32 v62, v39
	v_pk_fma_f32 v[58:59], v[58:59], v[58:59], v[60:61]
	v_mov_b32_e32 v60, v48
	v_mov_b32_e32 v61, v44
	v_pk_fma_f32 v[58:59], v[60:61], v[60:61], v[58:59]
	v_mov_b32_e32 v60, v49
	v_mov_b32_e32 v61, v45
	v_mov_b32_e32 v63, v35
	v_pk_fma_f32 v[58:59], v[60:61], v[60:61], v[58:59]
	v_mov_b32_e32 v60, v38
	v_mov_b32_e32 v61, v34
	v_pk_mul_f32 v[62:63], v[62:63], v[62:63]
	v_mov_b32_e32 v64, v31
	v_pk_fma_f32 v[60:61], v[60:61], v[60:61], v[62:63]
	v_mov_b32_e32 v62, v40
	v_mov_b32_e32 v63, v36
	v_pk_fma_f32 v[60:61], v[62:63], v[62:63], v[60:61]
	v_mov_b32_e32 v62, v41
	v_mov_b32_e32 v63, v37
	v_mov_b32_e32 v65, v27
	v_pk_fma_f32 v[60:61], v[62:63], v[62:63], v[60:61]
	v_mov_b32_e32 v62, v30
	v_mov_b32_e32 v63, v26
	v_pk_mul_f32 v[64:65], v[64:65], v[64:65]
	v_mov_b32_e32 v66, v23
	v_pk_fma_f32 v[62:63], v[62:63], v[62:63], v[64:65]
	v_mov_b32_e32 v64, v32
	v_mov_b32_e32 v65, v28
	v_pk_fma_f32 v[62:63], v[64:65], v[64:65], v[62:63]
	v_mov_b32_e32 v64, v33
	v_mov_b32_e32 v65, v29
	v_mov_b32_e32 v67, v19
	v_pk_fma_f32 v[62:63], v[64:65], v[64:65], v[62:63]
	v_mov_b32_e32 v64, v22
	v_mov_b32_e32 v65, v18
	v_pk_mul_f32 v[66:67], v[66:67], v[66:67]
	s_nop 0
	v_pk_fma_f32 v[64:65], v[64:65], v[64:65], v[66:67]
	v_mov_b32_e32 v66, v24
	v_mov_b32_e32 v67, v20
	v_pk_fma_f32 v[64:65], v[66:67], v[66:67], v[64:65]
	v_mov_b32_e32 v66, v25
	v_mov_b32_e32 v67, v21
	v_pk_fma_f32 v[64:65], v[66:67], v[66:67], v[64:65]
	v_mov_b32_e32 v66, v210
	v_mov_b32_e32 v67, v58
	v_lshlrev_b32_e32 v66, 2, v66
	v_xor_b32_e32 v68, 0x80, v66
	v_mov_b32_e32 v66, v210
	v_mov_b32_e32 v58, v61
	v_lshlrev_b32_e32 v66, 2, v66
	v_xor_b32_e32 v69, 0x80, v66
	v_mov_b32_e32 v66, v60
	v_pk_add_f32 v[58:59], v[66:67], v[58:59]
	v_mov_b32_e32 v60, v64
	v_mov_b32_e32 v61, v62
	v_pk_add_f32 v[58:59], v[58:59], v[60:61]
	v_mov_b32_e32 v62, v65
	v_pk_add_f32 v[58:59], v[58:59], v[62:63]
	ds_swizzle_b32 v61, v59 offset:swizzle(SWAP,16)
	ds_swizzle_b32 v60, v58 offset:swizzle(SWAP,16)
	s_waitcnt lgkmcnt(0)
	v_pk_add_f32 v[58:59], v[58:59], v[60:61]
	ds_swizzle_b32 v61, v59 offset:swizzle(SWAP,8)
	ds_swizzle_b32 v60, v58 offset:swizzle(SWAP,8)
	s_waitcnt lgkmcnt(0)
	v_pk_add_f32 v[58:59], v[58:59], v[60:61]
	ds_swizzle_b32 v61, v59 offset:swizzle(SWAP,4)
	ds_swizzle_b32 v60, v58 offset:swizzle(SWAP,4)
	s_waitcnt lgkmcnt(0)
	v_pk_add_f32 v[58:59], v[58:59], v[60:61]
	ds_swizzle_b32 v61, v59 offset:swizzle(SWAP,2)
	ds_swizzle_b32 v60, v58 offset:swizzle(SWAP,2)
	s_waitcnt lgkmcnt(0)
	v_pk_add_f32 v[58:59], v[58:59], v[60:61]
	ds_swizzle_b32 v61, v59 offset:swizzle(SWAP,1)
	ds_swizzle_b32 v60, v58 offset:swizzle(SWAP,1)
	s_waitcnt lgkmcnt(0)
	v_pk_add_f32 v[58:59], v[58:59], v[60:61]
	ds_bpermute_b32 v61, v68, v59
	ds_bpermute_b32 v60, v69, v58
	s_waitcnt lgkmcnt(0)
; __device__ __forceinline__ void store8bf(bf16_t* p, f32x4 v0, f32x4 v1) { u32x4 w; w.x = cvt_pk_bf16(v0[0], v0[1]); w.y = cvt_pk_bf16(v0[2], v0[3]); w.z = cvt_pk_bf16(v1[0], v1[1]); w.w = cvt_pk_bf16(v1[2], v1[3]); *(u32x4*)p = w; }
; template <int M> __device__ __forceinline__ float shx(float v) { return __builtin_bit_cast(float, __builtin_amdgcn_ds_swizzle(__builtin_bit_cast(int, v), (M << 10) | 0x1f)); }
; __device__ __forceinline__ float xhalf(float v) {
;   int l = (int)__builtin_amdgcn_mbcnt_hi(~0u, __builtin_amdgcn_mbcnt_lo(~0u, 0u)); asm volatile("" : "+v"(l));
;   return __builtin_bit_cast(float, __builtin_amdgcn_ds_bpermute((l ^ 32) << 2, __builtin_bit_cast(int, v))); }
; __device__ __forceinline__ float sum32(float v) { return v + xhalf(v); }
; __device__ __forceinline__ float max32(float v) { return __builtin_fmaxf(v, xhalf(v)); }
; __device__ __forceinline__ float wave_sum(float v) {
;   v += shx<16>(v); v += shx<8>(v); v += shx<4>(v); v += shx<2>(v); v += shx<1>(v); return sum32(v);
; }
; __device__ __forceinline__ void norm_phase(const float* H, const float* g, bf16_t* HN) {
;     ...
;   for (int row = gw; row < NREAL + 64; row += 2 * nw) {
;     const int row2 = row + nw < NREAL + 64 ? row + nw : row;
;     const float* p = H + (size_t)row * DM + lane * 8; const float* p2 = H + (size_t)row2 * DM + lane * 8; f32x4 v[4], u[4]; float ss = 0.f, ss2 = 0.f;
; #pragma unroll
;     for (int i = 0; i < 4; ++i) { v[i] = *(const f32x4*)(p + 512 * (i >> 1) + 4 * (i & 1)); u[i] = *(const f32x4*)(p2 + 512 * (i >> 1) + 4 * (i & 1)); }
; #pragma unroll
;     for (int i = 0; i < 4; ++i) { ss += v[i][0] * v[i][0] + v[i][1] * v[i][1] + v[i][2] * v[i][2] + v[i][3] * v[i][3]; ss2 += u[i][0] * u[i][0] + u[i][1] * u[i][1] + u[i][2] * u[i][2] + u[i][3] * u[i][3]; }
;     ss = wave_sum(ss); ss2 = wave_sum(ss2); const float rs = rsqrtf(ss * (1.0f / 1024.0f) + 1e-6f), rs2 = rsqrtf(ss2 * (1.0f / 1024.0f) + 1e-6f);
;     bf16_t* q = HN + (size_t)row * DM + lane * 8; bf16_t* q2 = HN + (size_t)row2 * DM + lane * 8;
; #pragma unroll
;     for (int i = 0; i < 2; ++i) { store8bf(q + 512 * i, v[2 * i] * rs * gv[2 * i], v[2 * i + 1] * rs * gv[2 * i + 1]); store8bf(q2 + 512 * i, u[2 * i] * rs2 * gv[2 * i], u[2 * i + 1] * rs2 * gv[2 * i + 1]); }
;   }
	v_pk_add_f32 v[58:59], v[58:59], v[60:61]
	s_nop 0
	v_pk_fma_f32 v[58:59], v[58:59], s[58:59], v[154:155] op_sel_hi:[1,0,0]
	s_nop 0
	v_mul_f32_e32 v60, 0x4b800000, v59
	v_cmp_gt_f32_e64 s[4:5], s46, v59
	v_cmp_gt_f32_e32 vcc, s46, v58
	s_nop 0
	v_cndmask_b32_e64 v59, v59, v60, s[4:5]
	v_rsq_f32_e32 v59, v59
	s_nop 0
	v_mul_f32_e32 v60, 0x45800000, v59
	v_cndmask_b32_e64 v60, v59, v60, s[4:5]
	v_mul_f32_e32 v59, 0x4b800000, v58
	v_cndmask_b32_e32 v58, v58, v59, vcc
	v_rsq_f32_e32 v58, v58
	v_pk_mul_f32 v[46:47], v[46:47], v[60:61] op_sel_hi:[1,0]
	v_pk_mul_f32 v[48:49], v[48:49], v[60:61] op_sel_hi:[1,0]
	v_pk_mul_f32 v[42:43], v[42:43], v[60:61] op_sel_hi:[1,0]
	v_mul_f32_e32 v59, 0x45800000, v58
	v_pk_mul_f32 v[44:45], v[44:45], v[60:61] op_sel_hi:[1,0]
	v_cndmask_b32_e32 v58, v58, v59, vcc
	v_pk_mul_f32 v[48:49], v[8:9], v[48:49]
	v_pk_mul_f32 v[46:47], v[6:7], v[46:47]
	v_pk_mul_f32 v[62:63], v[4:5], v[44:45]
	v_pk_mul_f32 v[44:45], v[2:3], v[42:43]
	v_cvt_pk_bf16_f32 v42, v46, v47
	v_cvt_pk_bf16_f32 v43, v48, v49
	v_cvt_pk_bf16_f32 v44, v44, v45
	v_cvt_pk_bf16_f32 v45, v62, v63
	v_pk_mul_f32 v[38:39], v[38:39], v[58:59] op_sel_hi:[1,0]
	v_pk_mul_f32 v[40:41], v[40:41], v[58:59] op_sel_hi:[1,0]
	v_pk_mul_f32 v[34:35], v[34:35], v[58:59] op_sel_hi:[1,0]
	v_pk_mul_f32 v[36:37], v[36:37], v[58:59] op_sel_hi:[1,0]
	global_store_dwordx4 v[54:55], v[42:45], off sc1
	v_pk_mul_f32 v[40:41], v[8:9], v[40:41]
	v_pk_mul_f32 v[38:39], v[6:7], v[38:39]
	v_pk_mul_f32 v[42:43], v[4:5], v[36:37]
	v_pk_mul_f32 v[36:37], v[2:3], v[34:35]
	v_cvt_pk_bf16_f32 v34, v38, v39
	v_cvt_pk_bf16_f32 v35, v40, v41
	v_cvt_pk_bf16_f32 v36, v36, v37
	v_cvt_pk_bf16_f32 v37, v42, v43
	v_pk_mul_f32 v[30:31], v[30:31], v[60:61] op_sel_hi:[1,0]
	v_pk_mul_f32 v[32:33], v[32:33], v[60:61] op_sel_hi:[1,0]
	v_pk_mul_f32 v[26:27], v[26:27], v[60:61] op_sel_hi:[1,0]
	v_pk_mul_f32 v[28:29], v[28:29], v[60:61] op_sel_hi:[1,0]
	global_store_dwordx4 v[56:57], v[34:37], off sc1
	v_pk_mul_f32 v[32:33], v[16:17], v[32:33]
	v_pk_mul_f32 v[30:31], v[14:15], v[30:31]
	v_pk_mul_f32 v[34:35], v[12:13], v[28:29]
	v_pk_mul_f32 v[28:29], v[10:11], v[26:27]
	v_cvt_pk_bf16_f32 v26, v30, v31
	v_cvt_pk_bf16_f32 v27, v32, v33
	v_cvt_pk_bf16_f32 v28, v28, v29
	v_cvt_pk_bf16_f32 v29, v34, v35
	global_store_dwordx4 v[54:55], v[26:29], off offset:1024 sc1
	v_pk_mul_f32 v[22:23], v[22:23], v[58:59] op_sel_hi:[1,0]
	v_pk_mul_f32 v[24:25], v[24:25], v[58:59] op_sel_hi:[1,0]
	v_pk_mul_f32 v[18:19], v[18:19], v[58:59] op_sel_hi:[1,0]
	v_pk_mul_f32 v[20:21], v[20:21], v[58:59] op_sel_hi:[1,0]
	v_pk_mul_f32 v[24:25], v[16:17], v[24:25]
	v_pk_mul_f32 v[22:23], v[14:15], v[22:23]
	v_pk_mul_f32 v[26:27], v[12:13], v[20:21]
	v_pk_mul_f32 v[20:21], v[10:11], v[18:19]
	v_cvt_pk_bf16_f32 v18, v22, v23
	v_cvt_pk_bf16_f32 v19, v24, v25
	v_cvt_pk_bf16_f32 v20, v20, v21
	v_cvt_pk_bf16_f32 v21, v26, v27
	global_store_dwordx4 v[56:57], v[18:21], off offset:1024 sc1
.Ln2_loop:
	s_add_i32 s0, s1, s8
	s_cmp_lt_i32 s0, s49
	s_cbranch_scc0 .Ln2_lastB
	s_add_i32 s9, s0, s24
	s_cmp_lt_i32 s9, s49
	s_cselect_b32 s9, s9, s0
	s_lshl_b32 s10, s0, 12
	s_lshl_b32 s4, s9, 12
	v_mov_b32_e32 v62, s10
	v_mov_b32_e32 v63, 0
	v_lshl_add_u64 v[58:59], v[50:51], 0, v[62:63]
	v_mov_b32_e32 v62, s4
	v_lshl_add_u64 v[60:61], v[50:51], 0, v[62:63]
	global_load_dwordx4 v[46:49], v[58:59], off
	global_load_dwordx4 v[42:45], v[58:59], off offset:16
	global_load_dwordx4 v[38:41], v[60:61], off
	global_load_dwordx4 v[34:37], v[60:61], off offset:16
	global_load_dwordx4 v[30:33], v[58:59], off offset:2048
	global_load_dwordx4 v[26:29], v[58:59], off offset:2064
	global_load_dwordx4 v[22:25], v[60:61], off offset:2048
	global_load_dwordx4 v[18:21], v[60:61], off offset:2064
	s_lshl_b32 s10, s0, 11
	s_lshl_b32 s4, s9, 11
	v_mov_b32_e32 v62, s10
	v_lshl_add_u64 v[54:55], v[52:53], 0, v[62:63]
	v_mov_b32_e32 v62, s4
	v_lshl_add_u64 v[56:57], v[52:53], 0, v[62:63]
	s_waitcnt vmcnt(12)
	v_mov_b32_e32 v60, v101
	v_mov_b32_e32 v61, v97
	v_mov_b32_e32 v58, v100
	v_mov_b32_e32 v59, v96
	v_pk_mul_f32 v[60:61], v[60:61], v[60:61]
	v_mov_b32_e32 v62, v93
	v_pk_fma_f32 v[58:59], v[58:59], v[58:59], v[60:61]
	v_mov_b32_e32 v60, v102
	v_mov_b32_e32 v61, v98
	v_pk_fma_f32 v[58:59], v[60:61], v[60:61], v[58:59]
	v_mov_b32_e32 v60, v103
	v_mov_b32_e32 v61, v99
	v_mov_b32_e32 v63, v89
	v_pk_fma_f32 v[58:59], v[60:61], v[60:61], v[58:59]
	v_mov_b32_e32 v60, v92
	v_mov_b32_e32 v61, v88
	v_pk_mul_f32 v[62:63], v[62:63], v[62:63]
	v_mov_b32_e32 v64, v83
	v_pk_fma_f32 v[60:61], v[60:61], v[60:61], v[62:63]
	v_mov_b32_e32 v62, v94
	v_mov_b32_e32 v63, v90
	v_pk_fma_f32 v[60:61], v[62:63], v[62:63], v[60:61]
	v_mov_b32_e32 v62, v95
	v_mov_b32_e32 v63, v91
	v_mov_b32_e32 v65, v79
	v_pk_fma_f32 v[60:61], v[62:63], v[62:63], v[60:61]
	v_mov_b32_e32 v62, v82
	v_mov_b32_e32 v63, v78
	v_pk_mul_f32 v[64:65], v[64:65], v[64:65]
	v_mov_b32_e32 v66, v75
	v_pk_fma_f32 v[62:63], v[62:63], v[62:63], v[64:65]
	v_mov_b32_e32 v64, v84
	v_mov_b32_e32 v65, v80
	v_pk_fma_f32 v[62:63], v[64:65], v[64:65], v[62:63]
	v_mov_b32_e32 v64, v85
	v_mov_b32_e32 v65, v81
	v_mov_b32_e32 v67, v71
	v_pk_fma_f32 v[62:63], v[64:65], v[64:65], v[62:63]
	v_mov_b32_e32 v64, v74
	v_mov_b32_e32 v65, v70
	v_pk_mul_f32 v[66:67], v[66:67], v[66:67]
	s_nop 0
	v_pk_fma_f32 v[64:65], v[64:65], v[64:65], v[66:67]
	v_mov_b32_e32 v66, v76
	v_mov_b32_e32 v67, v72
	v_pk_fma_f32 v[64:65], v[66:67], v[66:67], v[64:65]
	v_mov_b32_e32 v66, v77
	v_mov_b32_e32 v67, v73
	v_pk_fma_f32 v[64:65], v[66:67], v[66:67], v[64:65]
	v_mov_b32_e32 v66, v210
	v_mov_b32_e32 v67, v58
	v_lshlrev_b32_e32 v66, 2, v66
	v_xor_b32_e32 v68, 0x80, v66
	v_mov_b32_e32 v66, v210
	v_mov_b32_e32 v58, v61
	v_lshlrev_b32_e32 v66, 2, v66
	v_xor_b32_e32 v69, 0x80, v66
	v_mov_b32_e32 v66, v60
	v_pk_add_f32 v[58:59], v[66:67], v[58:59]
	v_mov_b32_e32 v60, v64
	v_mov_b32_e32 v61, v62
	v_pk_add_f32 v[58:59], v[58:59], v[60:61]
	v_mov_b32_e32 v62, v65
	v_pk_add_f32 v[58:59], v[58:59], v[62:63]
	ds_swizzle_b32 v61, v59 offset:swizzle(SWAP,16)
	ds_swizzle_b32 v60, v58 offset:swizzle(SWAP,16)
	s_waitcnt lgkmcnt(0)
; __device__ __forceinline__ void store8bf(bf16_t* p, f32x4 v0, f32x4 v1) { u32x4 w; w.x = cvt_pk_bf16(v0[0], v0[1]); w.y = cvt_pk_bf16(v0[2], v0[3]); w.z = cvt_pk_bf16(v1[0], v1[1]); w.w = cvt_pk_bf16(v1[2], v1[3]); *(u32x4*)p = w; }
; template <int M> __device__ __forceinline__ float shx(float v) { return __builtin_bit_cast(float, __builtin_amdgcn_ds_swizzle(__builtin_bit_cast(int, v), (M << 10) | 0x1f)); }
; __device__ __forceinline__ float xhalf(float v) {
;   int l = (int)__builtin_amdgcn_mbcnt_hi(~0u, __builtin_amdgcn_mbcnt_lo(~0u, 0u)); asm volatile("" : "+v"(l));
;   return __builtin_bit_cast(float, __builtin_amdgcn_ds_bpermute((l ^ 32) << 2, __builtin_bit_cast(int, v))); }
; __device__ __forceinline__ float sum32(float v) { return v + xhalf(v); }
; __device__ __forceinline__ float max32(float v) { return __builtin_fmaxf(v, xhalf(v)); }
; __device__ __forceinline__ float wave_sum(float v) {
;   v += shx<16>(v); v += shx<8>(v); v += shx<4>(v); v += shx<2>(v); v += shx<1>(v); return sum32(v);
; }
; __device__ __forceinline__ void norm_phase(const float* H, const float* g, bf16_t* HN) {
;     ...
;   for (int row = gw; row < NREAL + 64; row += 2 * nw) {
;     const int row2 = row + nw < NREAL + 64 ? row + nw : row;
;     const float* p = H + (size_t)row * DM + lane * 8; const float* p2 = H + (size_t)row2 * DM + lane * 8; f32x4 v[4], u[4]; float ss = 0.f, ss2 = 0.f;
; #pragma unroll
;     for (int i = 0; i < 4; ++i) { v[i] = *(const f32x4*)(p + 512 * (i >> 1) + 4 * (i & 1)); u[i] = *(const f32x4*)(p2 + 512 * (i >> 1) + 4 * (i & 1)); }
; #pragma unroll
;     for (int i = 0; i < 4; ++i) { ss += v[i][0] * v[i][0] + v[i][1] * v[i][1] + v[i][2] * v[i][2] + v[i][3] * v[i][3]; ss2 += u[i][0] * u[i][0] + u[i][1] * u[i][1] + u[i][2] * u[i][2] + u[i][3] * u[i][3]; }
;     ss = wave_sum(ss); ss2 = wave_sum(ss2); const float rs = rsqrtf(ss * (1.0f / 1024.0f) + 1e-6f), rs2 = rsqrtf(ss2 * (1.0f / 1024.0f) + 1e-6f);
;     bf16_t* q = HN + (size_t)row * DM + lane * 8; bf16_t* q2 = HN + (size_t)row2 * DM + lane * 8;
; #pragma unroll
;     for (int i = 0; i < 2; ++i) { store8bf(q + 512 * i, v[2 * i] * rs * gv[2 * i], v[2 * i + 1] * rs * gv[2 * i + 1]); store8bf(q2 + 512 * i, u[2 * i] * rs2 * gv[2 * i], u[2 * i + 1] * rs2 * gv[2 * i + 1]); }
;   }
	v_pk_add_f32 v[58:59], v[58:59], v[60:61]
	ds_swizzle_b32 v61, v59 offset:swizzle(SWAP,8)
	ds_swizzle_b32 v60, v58 offset:swizzle(SWAP,8)
	s_waitcnt lgkmcnt(0)
	v_pk_add_f32 v[58:59], v[58:59], v[60:61]
	ds_swizzle_b32 v61, v59 offset:swizzle(SWAP,4)
	ds_swizzle_b32 v60, v58 offset:swizzle(SWAP,4)
	s_waitcnt lgkmcnt(0)
	v_pk_add_f32 v[58:59], v[58:59], v[60:61]
	ds_swizzle_b32 v61, v59 offset:swizzle(SWAP,2)
	ds_swizzle_b32 v60, v58 offset:swizzle(SWAP,2)
	s_waitcnt lgkmcnt(0)
	v_pk_add_f32 v[58:59], v[58:59], v[60:61]
	ds_swizzle_b32 v61, v59 offset:swizzle(SWAP,1)
	ds_swizzle_b32 v60, v58 offset:swizzle(SWAP,1)
	s_waitcnt lgkmcnt(0)
	v_pk_add_f32 v[58:59], v[58:59], v[60:61]
	ds_bpermute_b32 v61, v68, v59
	ds_bpermute_b32 v60, v69, v58
	s_waitcnt lgkmcnt(0)
	v_pk_add_f32 v[58:59], v[58:59], v[60:61]
	s_nop 0
	v_pk_fma_f32 v[58:59], v[58:59], s[58:59], v[154:155] op_sel_hi:[1,0,0]
	s_nop 0
	v_mul_f32_e32 v60, 0x4b800000, v59
	v_cmp_gt_f32_e64 s[4:5], s46, v59
	v_cmp_gt_f32_e32 vcc, s46, v58
	s_nop 0
	v_cndmask_b32_e64 v59, v59, v60, s[4:5]
	v_rsq_f32_e32 v59, v59
	s_nop 0
	v_mul_f32_e32 v60, 0x45800000, v59
	v_cndmask_b32_e64 v60, v59, v60, s[4:5]
	v_mul_f32_e32 v59, 0x4b800000, v58
	v_cndmask_b32_e32 v58, v58, v59, vcc
	v_rsq_f32_e32 v58, v58
	v_pk_mul_f32 v[100:101], v[100:101], v[60:61] op_sel_hi:[1,0]
	v_pk_mul_f32 v[102:103], v[102:103], v[60:61] op_sel_hi:[1,0]
	v_pk_mul_f32 v[96:97], v[96:97], v[60:61] op_sel_hi:[1,0]
	v_mul_f32_e32 v59, 0x45800000, v58
	v_pk_mul_f32 v[98:99], v[98:99], v[60:61] op_sel_hi:[1,0]
	v_cndmask_b32_e32 v58, v58, v59, vcc
	v_pk_mul_f32 v[102:103], v[8:9], v[102:103]
	v_pk_mul_f32 v[100:101], v[6:7], v[100:101]
	v_pk_mul_f32 v[62:63], v[4:5], v[98:99]
	v_pk_mul_f32 v[98:99], v[2:3], v[96:97]
	v_cvt_pk_bf16_f32 v96, v100, v101
	v_cvt_pk_bf16_f32 v97, v102, v103
	v_cvt_pk_bf16_f32 v98, v98, v99
	v_cvt_pk_bf16_f32 v99, v62, v63
	v_pk_mul_f32 v[92:93], v[92:93], v[58:59] op_sel_hi:[1,0]
	v_pk_mul_f32 v[94:95], v[94:95], v[58:59] op_sel_hi:[1,0]
	v_pk_mul_f32 v[88:89], v[88:89], v[58:59] op_sel_hi:[1,0]
	v_pk_mul_f32 v[90:91], v[90:91], v[58:59] op_sel_hi:[1,0]
	global_store_dwordx4 v[128:129], v[96:99], off sc1
	v_pk_mul_f32 v[94:95], v[8:9], v[94:95]
	v_pk_mul_f32 v[92:93], v[6:7], v[92:93]
	v_pk_mul_f32 v[96:97], v[4:5], v[90:91]
	v_pk_mul_f32 v[90:91], v[2:3], v[88:89]
	v_cvt_pk_bf16_f32 v88, v92, v93
	v_cvt_pk_bf16_f32 v89, v94, v95
	v_cvt_pk_bf16_f32 v90, v90, v91
	v_cvt_pk_bf16_f32 v91, v96, v97
	v_pk_mul_f32 v[82:83], v[82:83], v[60:61] op_sel_hi:[1,0]
	v_pk_mul_f32 v[84:85], v[84:85], v[60:61] op_sel_hi:[1,0]
	v_pk_mul_f32 v[78:79], v[78:79], v[60:61] op_sel_hi:[1,0]
	v_pk_mul_f32 v[80:81], v[80:81], v[60:61] op_sel_hi:[1,0]
	global_store_dwordx4 v[130:131], v[88:91], off sc1
	v_pk_mul_f32 v[84:85], v[16:17], v[84:85]
	v_pk_mul_f32 v[82:83], v[14:15], v[82:83]
	v_pk_mul_f32 v[88:89], v[12:13], v[80:81]
	v_pk_mul_f32 v[80:81], v[10:11], v[78:79]
	v_cvt_pk_bf16_f32 v78, v82, v83
	v_cvt_pk_bf16_f32 v79, v84, v85
	v_cvt_pk_bf16_f32 v80, v80, v81
	v_cvt_pk_bf16_f32 v81, v88, v89
	global_store_dwordx4 v[128:129], v[78:81], off offset:1024 sc1
	v_pk_mul_f32 v[74:75], v[74:75], v[58:59] op_sel_hi:[1,0]
	v_pk_mul_f32 v[76:77], v[76:77], v[58:59] op_sel_hi:[1,0]
	v_pk_mul_f32 v[70:71], v[70:71], v[58:59] op_sel_hi:[1,0]
	v_pk_mul_f32 v[72:73], v[72:73], v[58:59] op_sel_hi:[1,0]
	v_pk_mul_f32 v[76:77], v[16:17], v[76:77]
	v_pk_mul_f32 v[74:75], v[14:15], v[74:75]
	v_pk_mul_f32 v[78:79], v[12:13], v[72:73]
	v_pk_mul_f32 v[72:73], v[10:11], v[70:71]
	v_cvt_pk_bf16_f32 v70, v74, v75
	v_cvt_pk_bf16_f32 v71, v76, v77
	v_cvt_pk_bf16_f32 v72, v72, v73
	v_cvt_pk_bf16_f32 v73, v78, v79
	global_store_dwordx4 v[130:131], v[70:73], off offset:1024 sc1
	s_add_i32 s1, s0, s8
	s_cmp_lt_i32 s1, s49
	s_cbranch_scc0 .Ln2_lastA
	s_add_i32 s9, s1, s24
	s_cmp_lt_i32 s9, s49
	s_cselect_b32 s9, s9, s1
	s_lshl_b32 s10, s1, 12
	s_lshl_b32 s4, s9, 12
	v_mov_b32_e32 v62, s10
	v_mov_b32_e32 v63, 0
	v_lshl_add_u64 v[58:59], v[50:51], 0, v[62:63]
	v_mov_b32_e32 v62, s4
	v_lshl_add_u64 v[60:61], v[50:51], 0, v[62:63]
	global_load_dwordx4 v[100:103], v[58:59], off
	global_load_dwordx4 v[96:99], v[58:59], off offset:16
	global_load_dwordx4 v[92:95], v[60:61], off
	global_load_dwordx4 v[88:91], v[60:61], off offset:16
	global_load_dwordx4 v[82:85], v[58:59], off offset:2048
	global_load_dwordx4 v[78:81], v[58:59], off offset:2064
	global_load_dwordx4 v[74:77], v[60:61], off offset:2048
	global_load_dwordx4 v[70:73], v[60:61], off offset:2064
	s_lshl_b32 s10, s1, 11
	s_lshl_b32 s4, s9, 11
	v_mov_b32_e32 v62, s10
	v_lshl_add_u64 v[128:129], v[52:53], 0, v[62:63]
	v_mov_b32_e32 v62, s4
	v_lshl_add_u64 v[130:131], v[52:53], 0, v[62:63]
	s_waitcnt vmcnt(12)
; __device__ __forceinline__ void store8bf(bf16_t* p, f32x4 v0, f32x4 v1) { u32x4 w; w.x = cvt_pk_bf16(v0[0], v0[1]); w.y = cvt_pk_bf16(v0[2], v0[3]); w.z = cvt_pk_bf16(v1[0], v1[1]); w.w = cvt_pk_bf16(v1[2], v1[3]); *(u32x4*)p = w; }
; template <int M> __device__ __forceinline__ float shx(float v) { return __builtin_bit_cast(float, __builtin_amdgcn_ds_swizzle(__builtin_bit_cast(int, v), (M << 10) | 0x1f)); }
; __device__ __forceinline__ float xhalf(float v) {
;   int l = (int)__builtin_amdgcn_mbcnt_hi(~0u, __builtin_amdgcn_mbcnt_lo(~0u, 0u)); asm volatile("" : "+v"(l));
;   return __builtin_bit_cast(float, __builtin_amdgcn_ds_bpermute((l ^ 32) << 2, __builtin_bit_cast(int, v))); }
; __device__ __forceinline__ float sum32(float v) { return v + xhalf(v); }
; __device__ __forceinline__ float max32(float v) { return __builtin_fmaxf(v, xhalf(v)); }
; __device__ __forceinline__ float wave_sum(float v) {
;   v += shx<16>(v); v += shx<8>(v); v += shx<4>(v); v += shx<2>(v); v += shx<1>(v); return sum32(v);
; }
; __device__ __forceinline__ void norm_phase(const float* H, const float* g, bf16_t* HN) {
;     ...
;   for (int row = gw; row < NREAL + 64; row += 2 * nw) {
;     const int row2 = row + nw < NREAL + 64 ? row + nw : row;
;     const float* p = H + (size_t)row * DM + lane * 8; const float* p2 = H + (size_t)row2 * DM + lane * 8; f32x4 v[4], u[4]; float ss = 0.f, ss2 = 0.f;
; #pragma unroll
;     for (int i = 0; i < 4; ++i) { v[i] = *(const f32x4*)(p + 512 * (i >> 1) + 4 * (i & 1)); u[i] = *(const f32x4*)(p2 + 512 * (i >> 1) + 4 * (i & 1)); }
; #pragma unroll
;     for (int i = 0; i < 4; ++i) { ss += v[i][0] * v[i][0] + v[i][1] * v[i][1] + v[i][2] * v[i][2] + v[i][3] * v[i][3]; ss2 += u[i][0] * u[i][0] + u[i][1] * u[i][1] + u[i][2] * u[i][2] + u[i][3] * u[i][3]; }
;     ss = wave_sum(ss); ss2 = wave_sum(ss2); const float rs = rsqrtf(ss * (1.0f / 1024.0f) + 1e-6f), rs2 = rsqrtf(ss2 * (1.0f / 1024.0f) + 1e-6f);
;     bf16_t* q = HN + (size_t)row * DM + lane * 8; bf16_t* q2 = HN + (size_t)row2 * DM + lane * 8;
; #pragma unroll
;     for (int i = 0; i < 2; ++i) { store8bf(q + 512 * i, v[2 * i] * rs * gv[2 * i], v[2 * i + 1] * rs * gv[2 * i + 1]); store8bf(q2 + 512 * i, u[2 * i] * rs2 * gv[2 * i], u[2 * i + 1] * rs2 * gv[2 * i + 1]); }
;   }
	v_mov_b32_e32 v60, v47
	v_mov_b32_e32 v61, v43
	v_mov_b32_e32 v58, v46
	v_mov_b32_e32 v59, v42
	v_pk_mul_f32 v[60:61], v[60:61], v[60:61]
	v_mov_b32_e32 v62, v39
	v_pk_fma_f32 v[58:59], v[58:59], v[58:59], v[60:61]
	v_mov_b32_e32 v60, v48
	v_mov_b32_e32 v61, v44
	v_pk_fma_f32 v[58:59], v[60:61], v[60:61], v[58:59]
	v_mov_b32_e32 v60, v49
	v_mov_b32_e32 v61, v45
	v_mov_b32_e32 v63, v35
	v_pk_fma_f32 v[58:59], v[60:61], v[60:61], v[58:59]
	v_mov_b32_e32 v60, v38
	v_mov_b32_e32 v61, v34
	v_pk_mul_f32 v[62:63], v[62:63], v[62:63]
	v_mov_b32_e32 v64, v31
	v_pk_fma_f32 v[60:61], v[60:61], v[60:61], v[62:63]
	v_mov_b32_e32 v62, v40
	v_mov_b32_e32 v63, v36
	v_pk_fma_f32 v[60:61], v[62:63], v[62:63], v[60:61]
	v_mov_b32_e32 v62, v41
	v_mov_b32_e32 v63, v37
	v_mov_b32_e32 v65, v27
	v_pk_fma_f32 v[60:61], v[62:63], v[62:63], v[60:61]
	v_mov_b32_e32 v62, v30
	v_mov_b32_e32 v63, v26
	v_pk_mul_f32 v[64:65], v[64:65], v[64:65]
	v_mov_b32_e32 v66, v23
	v_pk_fma_f32 v[62:63], v[62:63], v[62:63], v[64:65]
	v_mov_b32_e32 v64, v32
	v_mov_b32_e32 v65, v28
	v_pk_fma_f32 v[62:63], v[64:65], v[64:65], v[62:63]
	v_mov_b32_e32 v64, v33
	v_mov_b32_e32 v65, v29
	v_mov_b32_e32 v67, v19
	v_pk_fma_f32 v[62:63], v[64:65], v[64:65], v[62:63]
	v_mov_b32_e32 v64, v22
	v_mov_b32_e32 v65, v18
	v_pk_mul_f32 v[66:67], v[66:67], v[66:67]
	s_nop 0
	v_pk_fma_f32 v[64:65], v[64:65], v[64:65], v[66:67]
	v_mov_b32_e32 v66, v24
	v_mov_b32_e32 v67, v20
	v_pk_fma_f32 v[64:65], v[66:67], v[66:67], v[64:65]
	v_mov_b32_e32 v66, v25
	v_mov_b32_e32 v67, v21
	v_pk_fma_f32 v[64:65], v[66:67], v[66:67], v[64:65]
	v_mov_b32_e32 v66, v210
	v_mov_b32_e32 v67, v58
	v_lshlrev_b32_e32 v66, 2, v66
	v_xor_b32_e32 v68, 0x80, v66
	v_mov_b32_e32 v66, v210
	v_mov_b32_e32 v58, v61
	v_lshlrev_b32_e32 v66, 2, v66
	v_xor_b32_e32 v69, 0x80, v66
	v_mov_b32_e32 v66, v60
	v_pk_add_f32 v[58:59], v[66:67], v[58:59]
	v_mov_b32_e32 v60, v64
	v_mov_b32_e32 v61, v62
	v_pk_add_f32 v[58:59], v[58:59], v[60:61]
	v_mov_b32_e32 v62, v65
	v_pk_add_f32 v[58:59], v[58:59], v[62:63]
	ds_swizzle_b32 v61, v59 offset:swizzle(SWAP,16)
	ds_swizzle_b32 v60, v58 offset:swizzle(SWAP,16)
	s_waitcnt lgkmcnt(0)
	v_pk_add_f32 v[58:59], v[58:59], v[60:61]
	ds_swizzle_b32 v61, v59 offset:swizzle(SWAP,8)
	ds_swizzle_b32 v60, v58 offset:swizzle(SWAP,8)
	s_waitcnt lgkmcnt(0)
	v_pk_add_f32 v[58:59], v[58:59], v[60:61]
	ds_swizzle_b32 v61, v59 offset:swizzle(SWAP,4)
	ds_swizzle_b32 v60, v58 offset:swizzle(SWAP,4)
	s_waitcnt lgkmcnt(0)
	v_pk_add_f32 v[58:59], v[58:59], v[60:61]
	ds_swizzle_b32 v61, v59 offset:swizzle(SWAP,2)
	ds_swizzle_b32 v60, v58 offset:swizzle(SWAP,2)
	s_waitcnt lgkmcnt(0)
	v_pk_add_f32 v[58:59], v[58:59], v[60:61]
	ds_swizzle_b32 v61, v59 offset:swizzle(SWAP,1)
	ds_swizzle_b32 v60, v58 offset:swizzle(SWAP,1)
	s_waitcnt lgkmcnt(0)
	v_pk_add_f32 v[58:59], v[58:59], v[60:61]
	ds_bpermute_b32 v61, v68, v59
	ds_bpermute_b32 v60, v69, v58
	s_waitcnt lgkmcnt(0)
	v_pk_add_f32 v[58:59], v[58:59], v[60:61]
	s_nop 0
	v_pk_fma_f32 v[58:59], v[58:59], s[58:59], v[154:155] op_sel_hi:[1,0,0]
	s_nop 0
	v_mul_f32_e32 v60, 0x4b800000, v59
	v_cmp_gt_f32_e64 s[4:5], s46, v59
	v_cmp_gt_f32_e32 vcc, s46, v58
	s_nop 0
	v_cndmask_b32_e64 v59, v59, v60, s[4:5]
	v_rsq_f32_e32 v59, v59
	s_nop 0
	v_mul_f32_e32 v60, 0x45800000, v59
	v_cndmask_b32_e64 v60, v59, v60, s[4:5]
	v_mul_f32_e32 v59, 0x4b800000, v58
	v_cndmask_b32_e32 v58, v58, v59, vcc
	v_rsq_f32_e32 v58, v58
	v_pk_mul_f32 v[46:47], v[46:47], v[60:61] op_sel_hi:[1,0]
	v_pk_mul_f32 v[48:49], v[48:49], v[60:61] op_sel_hi:[1,0]
	v_pk_mul_f32 v[42:43], v[42:43], v[60:61] op_sel_hi:[1,0]
	v_mul_f32_e32 v59, 0x45800000, v58
	v_pk_mul_f32 v[44:45], v[44:45], v[60:61] op_sel_hi:[1,0]
	v_cndmask_b32_e32 v58, v58, v59, vcc
	v_pk_mul_f32 v[48:49], v[8:9], v[48:49]
	v_pk_mul_f32 v[46:47], v[6:7], v[46:47]
	v_pk_mul_f32 v[62:63], v[4:5], v[44:45]
	v_pk_mul_f32 v[44:45], v[2:3], v[42:43]
	v_cvt_pk_bf16_f32 v42, v46, v47
	v_cvt_pk_bf16_f32 v43, v48, v49
	v_cvt_pk_bf16_f32 v44, v44, v45
	v_cvt_pk_bf16_f32 v45, v62, v63
	v_pk_mul_f32 v[38:39], v[38:39], v[58:59] op_sel_hi:[1,0]
	v_pk_mul_f32 v[40:41], v[40:41], v[58:59] op_sel_hi:[1,0]
	v_pk_mul_f32 v[34:35], v[34:35], v[58:59] op_sel_hi:[1,0]
	v_pk_mul_f32 v[36:37], v[36:37], v[58:59] op_sel_hi:[1,0]
	global_store_dwordx4 v[54:55], v[42:45], off sc1
	v_pk_mul_f32 v[40:41], v[8:9], v[40:41]
	v_pk_mul_f32 v[38:39], v[6:7], v[38:39]
	v_pk_mul_f32 v[42:43], v[4:5], v[36:37]
	v_pk_mul_f32 v[36:37], v[2:3], v[34:35]
	v_cvt_pk_bf16_f32 v34, v38, v39
	v_cvt_pk_bf16_f32 v35, v40, v41
	v_cvt_pk_bf16_f32 v36, v36, v37
	v_cvt_pk_bf16_f32 v37, v42, v43
	v_pk_mul_f32 v[30:31], v[30:31], v[60:61] op_sel_hi:[1,0]
	v_pk_mul_f32 v[32:33], v[32:33], v[60:61] op_sel_hi:[1,0]
	v_pk_mul_f32 v[26:27], v[26:27], v[60:61] op_sel_hi:[1,0]
	v_pk_mul_f32 v[28:29], v[28:29], v[60:61] op_sel_hi:[1,0]
	global_store_dwordx4 v[56:57], v[34:37], off sc1
	v_pk_mul_f32 v[32:33], v[16:17], v[32:33]
	v_pk_mul_f32 v[30:31], v[14:15], v[30:31]
	v_pk_mul_f32 v[34:35], v[12:13], v[28:29]
	v_pk_mul_f32 v[28:29], v[10:11], v[26:27]
	v_cvt_pk_bf16_f32 v26, v30, v31
	v_cvt_pk_bf16_f32 v27, v32, v33
	v_cvt_pk_bf16_f32 v28, v28, v29
	v_cvt_pk_bf16_f32 v29, v34, v35
	global_store_dwordx4 v[54:55], v[26:29], off offset:1024 sc1
	v_pk_mul_f32 v[22:23], v[22:23], v[58:59] op_sel_hi:[1,0]
	v_pk_mul_f32 v[24:25], v[24:25], v[58:59] op_sel_hi:[1,0]
	v_pk_mul_f32 v[18:19], v[18:19], v[58:59] op_sel_hi:[1,0]
	v_pk_mul_f32 v[20:21], v[20:21], v[58:59] op_sel_hi:[1,0]
	v_pk_mul_f32 v[24:25], v[16:17], v[24:25]
	v_pk_mul_f32 v[22:23], v[14:15], v[22:23]
	v_pk_mul_f32 v[26:27], v[12:13], v[20:21]
	v_pk_mul_f32 v[20:21], v[10:11], v[18:19]
	v_cvt_pk_bf16_f32 v18, v22, v23
	v_cvt_pk_bf16_f32 v19, v24, v25
	v_cvt_pk_bf16_f32 v20, v20, v21
	v_cvt_pk_bf16_f32 v21, v26, v27
	global_store_dwordx4 v[56:57], v[18:21], off offset:1024 sc1
	s_branch .Ln2_loop
; __device__ __forceinline__ void store8bf(bf16_t* p, f32x4 v0, f32x4 v1) { u32x4 w; w.x = cvt_pk_bf16(v0[0], v0[1]); w.y = cvt_pk_bf16(v0[2], v0[3]); w.z = cvt_pk_bf16(v1[0], v1[1]); w.w = cvt_pk_bf16(v1[2], v1[3]); *(u32x4*)p = w; }
; template <int M> __device__ __forceinline__ float shx(float v) { return __builtin_bit_cast(float, __builtin_amdgcn_ds_swizzle(__builtin_bit_cast(int, v), (M << 10) | 0x1f)); }
; __device__ __forceinline__ float xhalf(float v) {
;   int l = (int)__builtin_amdgcn_mbcnt_hi(~0u, __builtin_amdgcn_mbcnt_lo(~0u, 0u)); asm volatile("" : "+v"(l));
;   return __builtin_bit_cast(float, __builtin_amdgcn_ds_bpermute((l ^ 32) << 2, __builtin_bit_cast(int, v))); }
; __device__ __forceinline__ float sum32(float v) { return v + xhalf(v); }
; __device__ __forceinline__ float max32(float v) { return __builtin_fmaxf(v, xhalf(v)); }
; __device__ __forceinline__ float wave_sum(float v) {
;   v += shx<16>(v); v += shx<8>(v); v += shx<4>(v); v += shx<2>(v); v += shx<1>(v); return sum32(v);
; }
; __device__ __forceinline__ void norm_phase(const float* H, const float* g, bf16_t* HN) {
;     ...
;   for (int row = gw; row < NREAL + 64; row += 2 * nw) {
;     const int row2 = row + nw < NREAL + 64 ? row + nw : row;
;     const float* p = H + (size_t)row * DM + lane * 8; const float* p2 = H + (size_t)row2 * DM + lane * 8; f32x4 v[4], u[4]; float ss = 0.f, ss2 = 0.f;
; #pragma unroll
;     for (int i = 0; i < 4; ++i) { v[i] = *(const f32x4*)(p + 512 * (i >> 1) + 4 * (i & 1)); u[i] = *(const f32x4*)(p2 + 512 * (i >> 1) + 4 * (i & 1)); }
; #pragma unroll
;     for (int i = 0; i < 4; ++i) { ss += v[i][0] * v[i][0] + v[i][1] * v[i][1] + v[i][2] * v[i][2] + v[i][3] * v[i][3]; ss2 += u[i][0] * u[i][0] + u[i][1] * u[i][1] + u[i][2] * u[i][2] + u[i][3] * u[i][3]; }
;     ss = wave_sum(ss); ss2 = wave_sum(ss2); const float rs = rsqrtf(ss * (1.0f / 1024.0f) + 1e-6f), rs2 = rsqrtf(ss2 * (1.0f / 1024.0f) + 1e-6f);
;     bf16_t* q = HN + (size_t)row * DM + lane * 8; bf16_t* q2 = HN + (size_t)row2 * DM + lane * 8;
; #pragma unroll
;     for (int i = 0; i < 2; ++i) { store8bf(q + 512 * i, v[2 * i] * rs * gv[2 * i], v[2 * i + 1] * rs * gv[2 * i + 1]); store8bf(q2 + 512 * i, u[2 * i] * rs2 * gv[2 * i], u[2 * i + 1] * rs2 * gv[2 * i + 1]); }
;   }
.Ln2_lastA_first:
	s_waitcnt vmcnt(0)
	v_mov_b32_e32 v60, v47
	v_mov_b32_e32 v61, v43
	v_mov_b32_e32 v58, v46
	v_mov_b32_e32 v59, v42
	v_pk_mul_f32 v[60:61], v[60:61], v[60:61]
	v_mov_b32_e32 v62, v39
	v_pk_fma_f32 v[58:59], v[58:59], v[58:59], v[60:61]
	v_mov_b32_e32 v60, v48
	v_mov_b32_e32 v61, v44
	v_pk_fma_f32 v[58:59], v[60:61], v[60:61], v[58:59]
	v_mov_b32_e32 v60, v49
	v_mov_b32_e32 v61, v45
	v_mov_b32_e32 v63, v35
	v_pk_fma_f32 v[58:59], v[60:61], v[60:61], v[58:59]
	v_mov_b32_e32 v60, v38
	v_mov_b32_e32 v61, v34
	v_pk_mul_f32 v[62:63], v[62:63], v[62:63]
	v_mov_b32_e32 v64, v31
	v_pk_fma_f32 v[60:61], v[60:61], v[60:61], v[62:63]
	v_mov_b32_e32 v62, v40
	v_mov_b32_e32 v63, v36
	v_pk_fma_f32 v[60:61], v[62:63], v[62:63], v[60:61]
	v_mov_b32_e32 v62, v41
	v_mov_b32_e32 v63, v37
	v_mov_b32_e32 v65, v27
	v_pk_fma_f32 v[60:61], v[62:63], v[62:63], v[60:61]
	v_mov_b32_e32 v62, v30
	v_mov_b32_e32 v63, v26
	v_pk_mul_f32 v[64:65], v[64:65], v[64:65]
	v_mov_b32_e32 v66, v23
	v_pk_fma_f32 v[62:63], v[62:63], v[62:63], v[64:65]
	v_mov_b32_e32 v64, v32
	v_mov_b32_e32 v65, v28
	v_pk_fma_f32 v[62:63], v[64:65], v[64:65], v[62:63]
	v_mov_b32_e32 v64, v33
	v_mov_b32_e32 v65, v29
	v_mov_b32_e32 v67, v19
	v_pk_fma_f32 v[62:63], v[64:65], v[64:65], v[62:63]
	v_mov_b32_e32 v64, v22
	v_mov_b32_e32 v65, v18
	v_pk_mul_f32 v[66:67], v[66:67], v[66:67]
	s_nop 0
	v_pk_fma_f32 v[64:65], v[64:65], v[64:65], v[66:67]
	v_mov_b32_e32 v66, v24
	v_mov_b32_e32 v67, v20
	v_pk_fma_f32 v[64:65], v[66:67], v[66:67], v[64:65]
	v_mov_b32_e32 v66, v25
	v_mov_b32_e32 v67, v21
	v_pk_fma_f32 v[64:65], v[66:67], v[66:67], v[64:65]
	v_mov_b32_e32 v66, v210
	v_mov_b32_e32 v67, v58
	v_lshlrev_b32_e32 v66, 2, v66
	v_xor_b32_e32 v68, 0x80, v66
	v_mov_b32_e32 v66, v210
	v_mov_b32_e32 v58, v61
	v_lshlrev_b32_e32 v66, 2, v66
	v_xor_b32_e32 v69, 0x80, v66
	v_mov_b32_e32 v66, v60
	v_pk_add_f32 v[58:59], v[66:67], v[58:59]
	v_mov_b32_e32 v60, v64
	v_mov_b32_e32 v61, v62
	v_pk_add_f32 v[58:59], v[58:59], v[60:61]
	v_mov_b32_e32 v62, v65
	v_pk_add_f32 v[58:59], v[58:59], v[62:63]
	ds_swizzle_b32 v61, v59 offset:swizzle(SWAP,16)
	ds_swizzle_b32 v60, v58 offset:swizzle(SWAP,16)
	s_waitcnt lgkmcnt(0)
	v_pk_add_f32 v[58:59], v[58:59], v[60:61]
	ds_swizzle_b32 v61, v59 offset:swizzle(SWAP,8)
	ds_swizzle_b32 v60, v58 offset:swizzle(SWAP,8)
	s_waitcnt lgkmcnt(0)
	v_pk_add_f32 v[58:59], v[58:59], v[60:61]
	ds_swizzle_b32 v61, v59 offset:swizzle(SWAP,4)
	ds_swizzle_b32 v60, v58 offset:swizzle(SWAP,4)
	s_waitcnt lgkmcnt(0)
	v_pk_add_f32 v[58:59], v[58:59], v[60:61]
	ds_swizzle_b32 v61, v59 offset:swizzle(SWAP,2)
	ds_swizzle_b32 v60, v58 offset:swizzle(SWAP,2)
	s_waitcnt lgkmcnt(0)
	v_pk_add_f32 v[58:59], v[58:59], v[60:61]
	ds_swizzle_b32 v61, v59 offset:swizzle(SWAP,1)
	ds_swizzle_b32 v60, v58 offset:swizzle(SWAP,1)
	s_waitcnt lgkmcnt(0)
	v_pk_add_f32 v[58:59], v[58:59], v[60:61]
	ds_bpermute_b32 v61, v68, v59
	ds_bpermute_b32 v60, v69, v58
	s_waitcnt lgkmcnt(0)
	v_pk_add_f32 v[58:59], v[58:59], v[60:61]
	s_nop 0
	v_pk_fma_f32 v[58:59], v[58:59], s[58:59], v[154:155] op_sel_hi:[1,0,0]
	s_nop 0
	v_mul_f32_e32 v60, 0x4b800000, v59
	v_cmp_gt_f32_e64 s[4:5], s46, v59
	v_cmp_gt_f32_e32 vcc, s46, v58
	s_nop 0
	v_cndmask_b32_e64 v59, v59, v60, s[4:5]
	v_rsq_f32_e32 v59, v59
	s_nop 0
	v_mul_f32_e32 v60, 0x45800000, v59
	v_cndmask_b32_e64 v60, v59, v60, s[4:5]
	v_mul_f32_e32 v59, 0x4b800000, v58
	v_cndmask_b32_e32 v58, v58, v59, vcc
	v_rsq_f32_e32 v58, v58
	v_pk_mul_f32 v[46:47], v[46:47], v[60:61] op_sel_hi:[1,0]
	v_pk_mul_f32 v[48:49], v[48:49], v[60:61] op_sel_hi:[1,0]
	v_pk_mul_f32 v[42:43], v[42:43], v[60:61] op_sel_hi:[1,0]
	v_mul_f32_e32 v59, 0x45800000, v58
	v_pk_mul_f32 v[44:45], v[44:45], v[60:61] op_sel_hi:[1,0]
	v_cndmask_b32_e32 v58, v58, v59, vcc
	v_pk_mul_f32 v[48:49], v[8:9], v[48:49]
	v_pk_mul_f32 v[46:47], v[6:7], v[46:47]
	v_pk_mul_f32 v[62:63], v[4:5], v[44:45]
	v_pk_mul_f32 v[44:45], v[2:3], v[42:43]
	v_cvt_pk_bf16_f32 v42, v46, v47
	v_cvt_pk_bf16_f32 v43, v48, v49
	v_cvt_pk_bf16_f32 v44, v44, v45
	v_cvt_pk_bf16_f32 v45, v62, v63
	v_pk_mul_f32 v[38:39], v[38:39], v[58:59] op_sel_hi:[1,0]
	v_pk_mul_f32 v[40:41], v[40:41], v[58:59] op_sel_hi:[1,0]
	v_pk_mul_f32 v[34:35], v[34:35], v[58:59] op_sel_hi:[1,0]
	v_pk_mul_f32 v[36:37], v[36:37], v[58:59] op_sel_hi:[1,0]
	global_store_dwordx4 v[54:55], v[42:45], off sc1
	v_pk_mul_f32 v[40:41], v[8:9], v[40:41]
	v_pk_mul_f32 v[38:39], v[6:7], v[38:39]
	v_pk_mul_f32 v[42:43], v[4:5], v[36:37]
	v_pk_mul_f32 v[36:37], v[2:3], v[34:35]
	v_cvt_pk_bf16_f32 v34, v38, v39
	v_cvt_pk_bf16_f32 v35, v40, v41
	v_cvt_pk_bf16_f32 v36, v36, v37
	v_cvt_pk_bf16_f32 v37, v42, v43
	v_pk_mul_f32 v[30:31], v[30:31], v[60:61] op_sel_hi:[1,0]
	v_pk_mul_f32 v[32:33], v[32:33], v[60:61] op_sel_hi:[1,0]
	v_pk_mul_f32 v[26:27], v[26:27], v[60:61] op_sel_hi:[1,0]
	v_pk_mul_f32 v[28:29], v[28:29], v[60:61] op_sel_hi:[1,0]
	global_store_dwordx4 v[56:57], v[34:37], off sc1
	v_pk_mul_f32 v[32:33], v[16:17], v[32:33]
	v_pk_mul_f32 v[30:31], v[14:15], v[30:31]
	v_pk_mul_f32 v[34:35], v[12:13], v[28:29]
	v_pk_mul_f32 v[28:29], v[10:11], v[26:27]
	v_cvt_pk_bf16_f32 v26, v30, v31
	v_cvt_pk_bf16_f32 v27, v32, v33
	v_cvt_pk_bf16_f32 v28, v28, v29
	v_cvt_pk_bf16_f32 v29, v34, v35
	global_store_dwordx4 v[54:55], v[26:29], off offset:1024 sc1
	v_pk_mul_f32 v[22:23], v[22:23], v[58:59] op_sel_hi:[1,0]
	v_pk_mul_f32 v[24:25], v[24:25], v[58:59] op_sel_hi:[1,0]
	v_pk_mul_f32 v[18:19], v[18:19], v[58:59] op_sel_hi:[1,0]
	v_pk_mul_f32 v[20:21], v[20:21], v[58:59] op_sel_hi:[1,0]
	v_pk_mul_f32 v[24:25], v[16:17], v[24:25]
	v_pk_mul_f32 v[22:23], v[14:15], v[22:23]
	v_pk_mul_f32 v[26:27], v[12:13], v[20:21]
	v_pk_mul_f32 v[20:21], v[10:11], v[18:19]
	v_cvt_pk_bf16_f32 v18, v22, v23
	v_cvt_pk_bf16_f32 v19, v24, v25
	v_cvt_pk_bf16_f32 v20, v20, v21
	v_cvt_pk_bf16_f32 v21, v26, v27
	global_store_dwordx4 v[56:57], v[18:21], off offset:1024 sc1
	s_branch .Ln2_done
; __device__ __forceinline__ void store8bf(bf16_t* p, f32x4 v0, f32x4 v1) { u32x4 w; w.x = cvt_pk_bf16(v0[0], v0[1]); w.y = cvt_pk_bf16(v0[2], v0[3]); w.z = cvt_pk_bf16(v1[0], v1[1]); w.w = cvt_pk_bf16(v1[2], v1[3]); *(u32x4*)p = w; }
; template <int M> __device__ __forceinline__ float shx(float v) { return __builtin_bit_cast(float, __builtin_amdgcn_ds_swizzle(__builtin_bit_cast(int, v), (M << 10) | 0x1f)); }
; __device__ __forceinline__ float xhalf(float v) {
;   int l = (int)__builtin_amdgcn_mbcnt_hi(~0u, __builtin_amdgcn_mbcnt_lo(~0u, 0u)); asm volatile("" : "+v"(l));
;   return __builtin_bit_cast(float, __builtin_amdgcn_ds_bpermute((l ^ 32) << 2, __builtin_bit_cast(int, v))); }
; __device__ __forceinline__ float sum32(float v) { return v + xhalf(v); }
; __device__ __forceinline__ float max32(float v) { return __builtin_fmaxf(v, xhalf(v)); }
; __device__ __forceinline__ float wave_sum(float v) {
;   v += shx<16>(v); v += shx<8>(v); v += shx<4>(v); v += shx<2>(v); v += shx<1>(v); return sum32(v);
; }
; __device__ __forceinline__ void norm_phase(const float* H, const float* g, bf16_t* HN) {
;     ...
;   for (int row = gw; row < NREAL + 64; row += 2 * nw) {
;     const int row2 = row + nw < NREAL + 64 ? row + nw : row;
;     const float* p = H + (size_t)row * DM + lane * 8; const float* p2 = H + (size_t)row2 * DM + lane * 8; f32x4 v[4], u[4]; float ss = 0.f, ss2 = 0.f;
; #pragma unroll
;     for (int i = 0; i < 4; ++i) { v[i] = *(const f32x4*)(p + 512 * (i >> 1) + 4 * (i & 1)); u[i] = *(const f32x4*)(p2 + 512 * (i >> 1) + 4 * (i & 1)); }
; #pragma unroll
;     for (int i = 0; i < 4; ++i) { ss += v[i][0] * v[i][0] + v[i][1] * v[i][1] + v[i][2] * v[i][2] + v[i][3] * v[i][3]; ss2 += u[i][0] * u[i][0] + u[i][1] * u[i][1] + u[i][2] * u[i][2] + u[i][3] * u[i][3]; }
;     ss = wave_sum(ss); ss2 = wave_sum(ss2); const float rs = rsqrtf(ss * (1.0f / 1024.0f) + 1e-6f), rs2 = rsqrtf(ss2 * (1.0f / 1024.0f) + 1e-6f);
;     bf16_t* q = HN + (size_t)row * DM + lane * 8; bf16_t* q2 = HN + (size_t)row2 * DM + lane * 8;
; #pragma unroll
;     for (int i = 0; i < 2; ++i) { store8bf(q + 512 * i, v[2 * i] * rs * gv[2 * i], v[2 * i + 1] * rs * gv[2 * i + 1]); store8bf(q2 + 512 * i, u[2 * i] * rs2 * gv[2 * i], u[2 * i + 1] * rs2 * gv[2 * i + 1]); }
;   }
.Ln2_lastB:
	s_waitcnt vmcnt(0)
	v_mov_b32_e32 v60, v101
	v_mov_b32_e32 v61, v97
	v_mov_b32_e32 v58, v100
	v_mov_b32_e32 v59, v96
	v_pk_mul_f32 v[60:61], v[60:61], v[60:61]
	v_mov_b32_e32 v62, v93
	v_pk_fma_f32 v[58:59], v[58:59], v[58:59], v[60:61]
	v_mov_b32_e32 v60, v102
	v_mov_b32_e32 v61, v98
	v_pk_fma_f32 v[58:59], v[60:61], v[60:61], v[58:59]
	v_mov_b32_e32 v60, v103
	v_mov_b32_e32 v61, v99
	v_mov_b32_e32 v63, v89
	v_pk_fma_f32 v[58:59], v[60:61], v[60:61], v[58:59]
	v_mov_b32_e32 v60, v92
	v_mov_b32_e32 v61, v88
	v_pk_mul_f32 v[62:63], v[62:63], v[62:63]
	v_mov_b32_e32 v64, v83
	v_pk_fma_f32 v[60:61], v[60:61], v[60:61], v[62:63]
	v_mov_b32_e32 v62, v94
	v_mov_b32_e32 v63, v90
	v_pk_fma_f32 v[60:61], v[62:63], v[62:63], v[60:61]
	v_mov_b32_e32 v62, v95
	v_mov_b32_e32 v63, v91
	v_mov_b32_e32 v65, v79
	v_pk_fma_f32 v[60:61], v[62:63], v[62:63], v[60:61]
	v_mov_b32_e32 v62, v82
	v_mov_b32_e32 v63, v78
	v_pk_mul_f32 v[64:65], v[64:65], v[64:65]
	v_mov_b32_e32 v66, v75
	v_pk_fma_f32 v[62:63], v[62:63], v[62:63], v[64:65]
	v_mov_b32_e32 v64, v84
	v_mov_b32_e32 v65, v80
	v_pk_fma_f32 v[62:63], v[64:65], v[64:65], v[62:63]
	v_mov_b32_e32 v64, v85
	v_mov_b32_e32 v65, v81
	v_mov_b32_e32 v67, v71
	v_pk_fma_f32 v[62:63], v[64:65], v[64:65], v[62:63]
	v_mov_b32_e32 v64, v74
	v_mov_b32_e32 v65, v70
	v_pk_mul_f32 v[66:67], v[66:67], v[66:67]
	s_nop 0
	v_pk_fma_f32 v[64:65], v[64:65], v[64:65], v[66:67]
	v_mov_b32_e32 v66, v76
	v_mov_b32_e32 v67, v72
	v_pk_fma_f32 v[64:65], v[66:67], v[66:67], v[64:65]
	v_mov_b32_e32 v66, v77
	v_mov_b32_e32 v67, v73
	v_pk_fma_f32 v[64:65], v[66:67], v[66:67], v[64:65]
	v_mov_b32_e32 v66, v210
	v_mov_b32_e32 v67, v58
	v_lshlrev_b32_e32 v66, 2, v66
	v_xor_b32_e32 v68, 0x80, v66
	v_mov_b32_e32 v66, v210
	v_mov_b32_e32 v58, v61
	v_lshlrev_b32_e32 v66, 2, v66
	v_xor_b32_e32 v69, 0x80, v66
	v_mov_b32_e32 v66, v60
	v_pk_add_f32 v[58:59], v[66:67], v[58:59]
	v_mov_b32_e32 v60, v64
	v_mov_b32_e32 v61, v62
	v_pk_add_f32 v[58:59], v[58:59], v[60:61]
	v_mov_b32_e32 v62, v65
	v_pk_add_f32 v[58:59], v[58:59], v[62:63]
	ds_swizzle_b32 v61, v59 offset:swizzle(SWAP,16)
	ds_swizzle_b32 v60, v58 offset:swizzle(SWAP,16)
	s_waitcnt lgkmcnt(0)
	v_pk_add_f32 v[58:59], v[58:59], v[60:61]
	ds_swizzle_b32 v61, v59 offset:swizzle(SWAP,8)
	ds_swizzle_b32 v60, v58 offset:swizzle(SWAP,8)
	s_waitcnt lgkmcnt(0)
	v_pk_add_f32 v[58:59], v[58:59], v[60:61]
	ds_swizzle_b32 v61, v59 offset:swizzle(SWAP,4)
	ds_swizzle_b32 v60, v58 offset:swizzle(SWAP,4)
	s_waitcnt lgkmcnt(0)
	v_pk_add_f32 v[58:59], v[58:59], v[60:61]
	ds_swizzle_b32 v61, v59 offset:swizzle(SWAP,2)
	ds_swizzle_b32 v60, v58 offset:swizzle(SWAP,2)
	s_waitcnt lgkmcnt(0)
	v_pk_add_f32 v[58:59], v[58:59], v[60:61]
	ds_swizzle_b32 v61, v59 offset:swizzle(SWAP,1)
	ds_swizzle_b32 v60, v58 offset:swizzle(SWAP,1)
	s_waitcnt lgkmcnt(0)
	v_pk_add_f32 v[58:59], v[58:59], v[60:61]
	ds_bpermute_b32 v61, v68, v59
	ds_bpermute_b32 v60, v69, v58
	s_waitcnt lgkmcnt(0)
	v_pk_add_f32 v[58:59], v[58:59], v[60:61]
	s_nop 0
	v_pk_fma_f32 v[58:59], v[58:59], s[58:59], v[154:155] op_sel_hi:[1,0,0]
	s_nop 0
	v_mul_f32_e32 v60, 0x4b800000, v59
	v_cmp_gt_f32_e64 s[4:5], s46, v59
	v_cmp_gt_f32_e32 vcc, s46, v58
	s_nop 0
	v_cndmask_b32_e64 v59, v59, v60, s[4:5]
	v_rsq_f32_e32 v59, v59
	s_nop 0
	v_mul_f32_e32 v60, 0x45800000, v59
	v_cndmask_b32_e64 v60, v59, v60, s[4:5]
	v_mul_f32_e32 v59, 0x4b800000, v58
	v_cndmask_b32_e32 v58, v58, v59, vcc
	v_rsq_f32_e32 v58, v58
	v_pk_mul_f32 v[100:101], v[100:101], v[60:61] op_sel_hi:[1,0]
	v_pk_mul_f32 v[102:103], v[102:103], v[60:61] op_sel_hi:[1,0]
	v_pk_mul_f32 v[96:97], v[96:97], v[60:61] op_sel_hi:[1,0]
	v_mul_f32_e32 v59, 0x45800000, v58
	v_pk_mul_f32 v[98:99], v[98:99], v[60:61] op_sel_hi:[1,0]
	v_cndmask_b32_e32 v58, v58, v59, vcc
	v_pk_mul_f32 v[102:103], v[8:9], v[102:103]
	v_pk_mul_f32 v[100:101], v[6:7], v[100:101]
	v_pk_mul_f32 v[62:63], v[4:5], v[98:99]
	v_pk_mul_f32 v[98:99], v[2:3], v[96:97]
	v_cvt_pk_bf16_f32 v96, v100, v101
	v_cvt_pk_bf16_f32 v97, v102, v103
	v_cvt_pk_bf16_f32 v98, v98, v99
	v_cvt_pk_bf16_f32 v99, v62, v63
	v_pk_mul_f32 v[92:93], v[92:93], v[58:59] op_sel_hi:[1,0]
	v_pk_mul_f32 v[94:95], v[94:95], v[58:59] op_sel_hi:[1,0]
	v_pk_mul_f32 v[88:89], v[88:89], v[58:59] op_sel_hi:[1,0]
	v_pk_mul_f32 v[90:91], v[90:91], v[58:59] op_sel_hi:[1,0]
	global_store_dwordx4 v[128:129], v[96:99], off sc1
	v_pk_mul_f32 v[94:95], v[8:9], v[94:95]
	v_pk_mul_f32 v[92:93], v[6:7], v[92:93]
	v_pk_mul_f32 v[96:97], v[4:5], v[90:91]
	v_pk_mul_f32 v[90:91], v[2:3], v[88:89]
	v_cvt_pk_bf16_f32 v88, v92, v93
	v_cvt_pk_bf16_f32 v89, v94, v95
	v_cvt_pk_bf16_f32 v90, v90, v91
	v_cvt_pk_bf16_f32 v91, v96, v97
	v_pk_mul_f32 v[82:83], v[82:83], v[60:61] op_sel_hi:[1,0]
	v_pk_mul_f32 v[84:85], v[84:85], v[60:61] op_sel_hi:[1,0]
	v_pk_mul_f32 v[78:79], v[78:79], v[60:61] op_sel_hi:[1,0]
	v_pk_mul_f32 v[80:81], v[80:81], v[60:61] op_sel_hi:[1,0]
	global_store_dwordx4 v[130:131], v[88:91], off sc1
	v_pk_mul_f32 v[84:85], v[16:17], v[84:85]
	v_pk_mul_f32 v[82:83], v[14:15], v[82:83]
	v_pk_mul_f32 v[88:89], v[12:13], v[80:81]
	v_pk_mul_f32 v[80:81], v[10:11], v[78:79]
	v_cvt_pk_bf16_f32 v78, v82, v83
	v_cvt_pk_bf16_f32 v79, v84, v85
	v_cvt_pk_bf16_f32 v80, v80, v81
	v_cvt_pk_bf16_f32 v81, v88, v89
	global_store_dwordx4 v[128:129], v[78:81], off offset:1024 sc1
	v_pk_mul_f32 v[74:75], v[74:75], v[58:59] op_sel_hi:[1,0]
	v_pk_mul_f32 v[76:77], v[76:77], v[58:59] op_sel_hi:[1,0]
	v_pk_mul_f32 v[70:71], v[70:71], v[58:59] op_sel_hi:[1,0]
	v_pk_mul_f32 v[72:73], v[72:73], v[58:59] op_sel_hi:[1,0]
	v_pk_mul_f32 v[76:77], v[16:17], v[76:77]
	v_pk_mul_f32 v[74:75], v[14:15], v[74:75]
	v_pk_mul_f32 v[78:79], v[12:13], v[72:73]
	v_pk_mul_f32 v[72:73], v[10:11], v[70:71]
	v_cvt_pk_bf16_f32 v70, v74, v75
	v_cvt_pk_bf16_f32 v71, v76, v77
	v_cvt_pk_bf16_f32 v72, v72, v73
	v_cvt_pk_bf16_f32 v73, v78, v79
	global_store_dwordx4 v[130:131], v[70:73], off offset:1024 sc1
	s_branch .Ln2_done
; __device__ __forceinline__ void store8bf(bf16_t* p, f32x4 v0, f32x4 v1) { u32x4 w; w.x = cvt_pk_bf16(v0[0], v0[1]); w.y = cvt_pk_bf16(v0[2], v0[3]); w.z = cvt_pk_bf16(v1[0], v1[1]); w.w = cvt_pk_bf16(v1[2], v1[3]); *(u32x4*)p = w; }
; template <int M> __device__ __forceinline__ float shx(float v) { return __builtin_bit_cast(float, __builtin_amdgcn_ds_swizzle(__builtin_bit_cast(int, v), (M << 10) | 0x1f)); }
; __device__ __forceinline__ float xhalf(float v) {
;   int l = (int)__builtin_amdgcn_mbcnt_hi(~0u, __builtin_amdgcn_mbcnt_lo(~0u, 0u)); asm volatile("" : "+v"(l));
;   return __builtin_bit_cast(float, __builtin_amdgcn_ds_bpermute((l ^ 32) << 2, __builtin_bit_cast(int, v))); }
; __device__ __forceinline__ float sum32(float v) { return v + xhalf(v); }
; __device__ __forceinline__ float max32(float v) { return __builtin_fmaxf(v, xhalf(v)); }
; __device__ __forceinline__ float wave_sum(float v) {
;   v += shx<16>(v); v += shx<8>(v); v += shx<4>(v); v += shx<2>(v); v += shx<1>(v); return sum32(v);
; }
; __device__ __forceinline__ void norm_phase(const float* H, const float* g, bf16_t* HN) {
;     ...
;   for (int row = gw; row < NREAL + 64; row += 2 * nw) {
;     const int row2 = row + nw < NREAL + 64 ? row + nw : row;
;     const float* p = H + (size_t)row * DM + lane * 8; const float* p2 = H + (size_t)row2 * DM + lane * 8; f32x4 v[4], u[4]; float ss = 0.f, ss2 = 0.f;
; #pragma unroll
;     for (int i = 0; i < 4; ++i) { v[i] = *(const f32x4*)(p + 512 * (i >> 1) + 4 * (i & 1)); u[i] = *(const f32x4*)(p2 + 512 * (i >> 1) + 4 * (i & 1)); }
; #pragma unroll
;     for (int i = 0; i < 4; ++i) { ss += v[i][0] * v[i][0] + v[i][1] * v[i][1] + v[i][2] * v[i][2] + v[i][3] * v[i][3]; ss2 += u[i][0] * u[i][0] + u[i][1] * u[i][1] + u[i][2] * u[i][2] + u[i][3] * u[i][3]; }
;     ss = wave_sum(ss); ss2 = wave_sum(ss2); const float rs = rsqrtf(ss * (1.0f / 1024.0f) + 1e-6f), rs2 = rsqrtf(ss2 * (1.0f / 1024.0f) + 1e-6f);
;     bf16_t* q = HN + (size_t)row * DM + lane * 8; bf16_t* q2 = HN + (size_t)row2 * DM + lane * 8;
; #pragma unroll
;     for (int i = 0; i < 2; ++i) { store8bf(q + 512 * i, v[2 * i] * rs * gv[2 * i], v[2 * i + 1] * rs * gv[2 * i + 1]); store8bf(q2 + 512 * i, u[2 * i] * rs2 * gv[2 * i], u[2 * i + 1] * rs2 * gv[2 * i + 1]); }
;   }
.Ln2_lastA:
	s_waitcnt vmcnt(0)
	v_mov_b32_e32 v60, v47
	v_mov_b32_e32 v61, v43
	v_mov_b32_e32 v58, v46
	v_mov_b32_e32 v59, v42
	v_pk_mul_f32 v[60:61], v[60:61], v[60:61]
	v_mov_b32_e32 v62, v39
	v_pk_fma_f32 v[58:59], v[58:59], v[58:59], v[60:61]
	v_mov_b32_e32 v60, v48
	v_mov_b32_e32 v61, v44
	v_pk_fma_f32 v[58:59], v[60:61], v[60:61], v[58:59]
	v_mov_b32_e32 v60, v49
	v_mov_b32_e32 v61, v45
	v_mov_b32_e32 v63, v35
	v_pk_fma_f32 v[58:59], v[60:61], v[60:61], v[58:59]
	v_mov_b32_e32 v60, v38
	v_mov_b32_e32 v61, v34
	v_pk_mul_f32 v[62:63], v[62:63], v[62:63]
	v_mov_b32_e32 v64, v31
	v_pk_fma_f32 v[60:61], v[60:61], v[60:61], v[62:63]
	v_mov_b32_e32 v62, v40
	v_mov_b32_e32 v63, v36
	v_pk_fma_f32 v[60:61], v[62:63], v[62:63], v[60:61]
	v_mov_b32_e32 v62, v41
	v_mov_b32_e32 v63, v37
	v_mov_b32_e32 v65, v27
	v_pk_fma_f32 v[60:61], v[62:63], v[62:63], v[60:61]
	v_mov_b32_e32 v62, v30
	v_mov_b32_e32 v63, v26
	v_pk_mul_f32 v[64:65], v[64:65], v[64:65]
	v_mov_b32_e32 v66, v23
	v_pk_fma_f32 v[62:63], v[62:63], v[62:63], v[64:65]
	v_mov_b32_e32 v64, v32
	v_mov_b32_e32 v65, v28
	v_pk_fma_f32 v[62:63], v[64:65], v[64:65], v[62:63]
	v_mov_b32_e32 v64, v33
	v_mov_b32_e32 v65, v29
	v_mov_b32_e32 v67, v19
	v_pk_fma_f32 v[62:63], v[64:65], v[64:65], v[62:63]
	v_mov_b32_e32 v64, v22
	v_mov_b32_e32 v65, v18
	v_pk_mul_f32 v[66:67], v[66:67], v[66:67]
	s_nop 0
	v_pk_fma_f32 v[64:65], v[64:65], v[64:65], v[66:67]
	v_mov_b32_e32 v66, v24
	v_mov_b32_e32 v67, v20
	v_pk_fma_f32 v[64:65], v[66:67], v[66:67], v[64:65]
	v_mov_b32_e32 v66, v25
	v_mov_b32_e32 v67, v21
	v_pk_fma_f32 v[64:65], v[66:67], v[66:67], v[64:65]
	v_mov_b32_e32 v66, v210
	v_mov_b32_e32 v67, v58
	v_lshlrev_b32_e32 v66, 2, v66
	v_xor_b32_e32 v68, 0x80, v66
	v_mov_b32_e32 v66, v210
	v_mov_b32_e32 v58, v61
	v_lshlrev_b32_e32 v66, 2, v66
	v_xor_b32_e32 v69, 0x80, v66
	v_mov_b32_e32 v66, v60
	v_pk_add_f32 v[58:59], v[66:67], v[58:59]
	v_mov_b32_e32 v60, v64
	v_mov_b32_e32 v61, v62
	v_pk_add_f32 v[58:59], v[58:59], v[60:61]
	v_mov_b32_e32 v62, v65
	v_pk_add_f32 v[58:59], v[58:59], v[62:63]
	ds_swizzle_b32 v61, v59 offset:swizzle(SWAP,16)
	ds_swizzle_b32 v60, v58 offset:swizzle(SWAP,16)
	s_waitcnt lgkmcnt(0)
	v_pk_add_f32 v[58:59], v[58:59], v[60:61]
	ds_swizzle_b32 v61, v59 offset:swizzle(SWAP,8)
	ds_swizzle_b32 v60, v58 offset:swizzle(SWAP,8)
	s_waitcnt lgkmcnt(0)
	v_pk_add_f32 v[58:59], v[58:59], v[60:61]
	ds_swizzle_b32 v61, v59 offset:swizzle(SWAP,4)
	ds_swizzle_b32 v60, v58 offset:swizzle(SWAP,4)
	s_waitcnt lgkmcnt(0)
	v_pk_add_f32 v[58:59], v[58:59], v[60:61]
	ds_swizzle_b32 v61, v59 offset:swizzle(SWAP,2)
	ds_swizzle_b32 v60, v58 offset:swizzle(SWAP,2)
	s_waitcnt lgkmcnt(0)
	v_pk_add_f32 v[58:59], v[58:59], v[60:61]
	ds_swizzle_b32 v61, v59 offset:swizzle(SWAP,1)
	ds_swizzle_b32 v60, v58 offset:swizzle(SWAP,1)
	s_waitcnt lgkmcnt(0)
	v_pk_add_f32 v[58:59], v[58:59], v[60:61]
	ds_bpermute_b32 v61, v68, v59
	ds_bpermute_b32 v60, v69, v58
	s_waitcnt lgkmcnt(0)
	v_pk_add_f32 v[58:59], v[58:59], v[60:61]
	s_nop 0
	v_pk_fma_f32 v[58:59], v[58:59], s[58:59], v[154:155] op_sel_hi:[1,0,0]
	s_nop 0
	v_mul_f32_e32 v60, 0x4b800000, v59
	v_cmp_gt_f32_e64 s[4:5], s46, v59
	v_cmp_gt_f32_e32 vcc, s46, v58
	s_nop 0
	v_cndmask_b32_e64 v59, v59, v60, s[4:5]
	v_rsq_f32_e32 v59, v59
	s_nop 0
	v_mul_f32_e32 v60, 0x45800000, v59
	v_cndmask_b32_e64 v60, v59, v60, s[4:5]
	v_mul_f32_e32 v59, 0x4b800000, v58
	v_cndmask_b32_e32 v58, v58, v59, vcc
	v_rsq_f32_e32 v58, v58
	v_pk_mul_f32 v[46:47], v[46:47], v[60:61] op_sel_hi:[1,0]
	v_pk_mul_f32 v[48:49], v[48:49], v[60:61] op_sel_hi:[1,0]
	v_pk_mul_f32 v[42:43], v[42:43], v[60:61] op_sel_hi:[1,0]
	v_mul_f32_e32 v59, 0x45800000, v58
	v_pk_mul_f32 v[44:45], v[44:45], v[60:61] op_sel_hi:[1,0]
	v_cndmask_b32_e32 v58, v58, v59, vcc
	v_pk_mul_f32 v[48:49], v[8:9], v[48:49]
	v_pk_mul_f32 v[46:47], v[6:7], v[46:47]
	v_pk_mul_f32 v[62:63], v[4:5], v[44:45]
	v_pk_mul_f32 v[44:45], v[2:3], v[42:43]
	v_cvt_pk_bf16_f32 v42, v46, v47
	v_cvt_pk_bf16_f32 v43, v48, v49
	v_cvt_pk_bf16_f32 v44, v44, v45
	v_cvt_pk_bf16_f32 v45, v62, v63
	v_pk_mul_f32 v[38:39], v[38:39], v[58:59] op_sel_hi:[1,0]
	v_pk_mul_f32 v[40:41], v[40:41], v[58:59] op_sel_hi:[1,0]
	v_pk_mul_f32 v[34:35], v[34:35], v[58:59] op_sel_hi:[1,0]
	v_pk_mul_f32 v[36:37], v[36:37], v[58:59] op_sel_hi:[1,0]
	global_store_dwordx4 v[54:55], v[42:45], off sc1
	v_pk_mul_f32 v[40:41], v[8:9], v[40:41]
	v_pk_mul_f32 v[38:39], v[6:7], v[38:39]
	v_pk_mul_f32 v[42:43], v[4:5], v[36:37]
	v_pk_mul_f32 v[36:37], v[2:3], v[34:35]
	v_cvt_pk_bf16_f32 v34, v38, v39
	v_cvt_pk_bf16_f32 v35, v40, v41
	v_cvt_pk_bf16_f32 v36, v36, v37
	v_cvt_pk_bf16_f32 v37, v42, v43
	v_pk_mul_f32 v[30:31], v[30:31], v[60:61] op_sel_hi:[1,0]
	v_pk_mul_f32 v[32:33], v[32:33], v[60:61] op_sel_hi:[1,0]
	v_pk_mul_f32 v[26:27], v[26:27], v[60:61] op_sel_hi:[1,0]
	v_pk_mul_f32 v[28:29], v[28:29], v[60:61] op_sel_hi:[1,0]
	global_store_dwordx4 v[56:57], v[34:37], off sc1
	v_pk_mul_f32 v[32:33], v[16:17], v[32:33]
	v_pk_mul_f32 v[30:31], v[14:15], v[30:31]
	v_pk_mul_f32 v[34:35], v[12:13], v[28:29]
	v_pk_mul_f32 v[28:29], v[10:11], v[26:27]
	v_cvt_pk_bf16_f32 v26, v30, v31
	v_cvt_pk_bf16_f32 v27, v32, v33
	v_cvt_pk_bf16_f32 v28, v28, v29
	v_cvt_pk_bf16_f32 v29, v34, v35
	global_store_dwordx4 v[54:55], v[26:29], off offset:1024 sc1
	v_pk_mul_f32 v[22:23], v[22:23], v[58:59] op_sel_hi:[1,0]
	v_pk_mul_f32 v[24:25], v[24:25], v[58:59] op_sel_hi:[1,0]
	v_pk_mul_f32 v[18:19], v[18:19], v[58:59] op_sel_hi:[1,0]
	v_pk_mul_f32 v[20:21], v[20:21], v[58:59] op_sel_hi:[1,0]
	v_pk_mul_f32 v[24:25], v[16:17], v[24:25]
	v_pk_mul_f32 v[22:23], v[14:15], v[22:23]
	v_pk_mul_f32 v[26:27], v[12:13], v[20:21]
	v_pk_mul_f32 v[20:21], v[10:11], v[18:19]
	v_cvt_pk_bf16_f32 v18, v22, v23
	v_cvt_pk_bf16_f32 v19, v24, v25
	v_cvt_pk_bf16_f32 v20, v20, v21
	v_cvt_pk_bf16_f32 v21, v26, v27
	global_store_dwordx4 v[56:57], v[18:21], off offset:1024 sc1
